# attention loop: 19 leftover s_nop (pads the compiler placed around the removed inline-asm adds and a bank-swap-obsolete 8-state pad) and 6 dead VALU (mrun+8 / -mrun helpers, x+0 adds) removed per pair
# speedup vs baseline: 1.0022x; 1.0022x over previous
; #define ATT_LOAD(k0_, k1_, v_, tt) do { const char* kg_ = Kg + (size_t)(tt) * 12288; const char* vg_ = Vg + (size_t)(tt) * 8192; \
;             k0_ = *(const u32x4*)(kg_ + tid_ * 16); if (tid_ < 256) k1_ = *(const u32x4*)(kg_ + (tid_ + 512) * 16); v_ = *(const u32x4*)(vg_ + tid_ * 16); } while (0)
; #define ATT_WRITE(k0_, k1_, v_, bo) do { *(LAS u32x4*)(sm + (bo) + koff0) = k0_; if (tid_ < 256) *(LAS u32x4*)(sm + (bo) + koff1) = k1_; *(LAS u32x4*)(sm + (bo) + voff) = v_; } while (0)
; __device__ __forceinline__ void att_shift(float tm, bool first, float& mrun, float& lsum, fa::f32x16& o0, fa::f32x16& o1) {
;     if (first || __any(tm > mrun + 8.f)) {
;         tm = fmaxf(tm, __shfl_xor(tm, 32));
; __device__ __forceinline__ void ph_attn_mfma(unsigned char* lds_, const bf16_t* Q, const bf16_t* Kb, const bf16_t* Vb, bf16_t* Z, int with_ctx, int u0, int ustep) { PH_IDS;
;     ...
;         for (int p = 0; p < npair; ++p) {
;             const int nxt = cur == 4 * BUF_A ? 0 : cur + 2 * BUF_A;
;             const bool more = p + 1 < npair;
;             if (more) { ATT_WRITE(ka0, ka1, va, nxt); ATT_WRITE(kb0, kb1, vb, nxt + BUF_A); }
;             if (p + 2 < npair) { ATT_LOAD(ka0, ka1, va, 2 * p + 4); ATT_LOAD(kb0, kb1, vb, 2 * p + 5); }
;             bf16x8 pf[4];
;             att_shift(tmA, p == 0, mrun, lsum, o0, o1);
;             att_qk_exp(sm + cur + BUF_A + r32 * KP_A + 16 * hi, qf, -mrun, b0, b1, a0, a1, lsum, pf);
;             const float tmB = att_pv_max(o0, o1, sm + cur + vrd, pf, b0, b1);
;             att_shift(tmB, false, mrun, lsum, o0, o1);
.LBB0_1027:
	s_xor_b64 s[10:11], s[12:13], -1
	s_add_i32 s9, s8, 0xa800
	s_cmp_lg_u32 s8, 0x15000
	s_cselect_b32 s18, s9, 0
	s_and_b64 vcc, exec, s[10:11]
	s_mov_b64 s[14:15], 0
	s_mov_b64 s[16:17], -1
	s_cbranch_vccz .LBB0_1039
	v_cmp_lt_f32_e32 vcc, 0x41000000, v191
	s_cmp_lg_u64 vcc, 0
	s_cselect_b64 s[14:15], -1, 0
	s_cbranch_execz .LBB0_1040

; #define LAS __attribute__((address_space(3)))
; __device__ __forceinline__ bf16x8 pack_p(const f32x16& p, int base) { u32x4 w; w.x = pk2(p[base], p[base + 1]); w.y = pk2(p[base + 2], p[base + 3]); w.z = pk2(p[base + 4], p[base + 5]); w.w = pk2(p[base + 6], p[base + 7]); return __builtin_bit_cast(bf16x8, w); }
; __device__ __forceinline__ float vadd1(float a, float b) { float r; asm("v_add_f32 %0, %1, %2" : "=v"(r) : "v"(a), "v"(b)); return r; }
; __device__ __forceinline__ void att_shift(float tm, bool first, float& mrun, float& lsum, fa::f32x16& o0, fa::f32x16& o1) {
;     if (first || __any(tm > mrun + 8.f)) {
;         tm = fmaxf(tm, __shfl_xor(tm, 32));
;         const float dl = first ? 0.f : fmaxf(tm - mrun, 0.f), alpha = __builtin_amdgcn_exp2f(-dl);
;         mrun = first ? tm : mrun + dl; lsum *= alpha;
; #pragma unroll
;         for (int r = 0; r < 16; ++r) { o0[r] *= alpha; o1[r] *= alpha; }
;     }
; }
; __device__ __forceinline__ void att_qk_exp(const LAS char* kb, const bf16x8 (&qf)[6], float nm, fa::f32x16& n0, fa::f32x16& n1, fa::f32x16& p0, fa::f32x16& p1, float& lsum, bf16x8 (&pf)[4]) {
;     const fa::f32x16 zero = {0.f, 0.f, 0.f, 0.f, 0.f, 0.f, 0.f, 0.f, 0.f, 0.f, 0.f, 0.f, 0.f, 0.f, 0.f, 0.f};
;     bf16x8 kc0 = *(const LAS bf16x8*)kb, kc1 = *(const LAS bf16x8*)(kb + 32 * fa::KP_A);
;     float ps = 0.f, ps2 = 0.f;
; #pragma unroll
;     for (int st = 0; st < 6; ++st) {
;         bf16x8 kn0 = kc0, kn1 = kc1;
;         if (st < 5) { kn0 = *(const LAS bf16x8*)(kb + 32 * (st + 1)); kn1 = *(const LAS bf16x8*)(kb + 32 * fa::KP_A + 32 * (st + 1)); }
;         n0 = __builtin_amdgcn_mfma_f32_32x32x16_bf16(kc0, qf[st], st == 0 ? zero : n0, 0, 0, 0);
;         n1 = __builtin_amdgcn_mfma_f32_32x32x16_bf16(kc1, qf[st], st == 0 ? zero : n1, 0, 0, 0);
;         constexpr int lo[7] = {0, 2, 6, 8, 10, 14, 16};
; #pragma unroll
;         for (int r = lo[st]; r < lo[st + 1]; ++r) {
;             p0[r] = __builtin_amdgcn_exp2f(vadd1(p0[r], nm)); p1[r] = __builtin_amdgcn_exp2f(vadd1(p1[r], nm));
;             ps += p0[r]; ps += p1[r]; }
;         kc0 = kn0; kc1 = kn1;
;         __builtin_amdgcn_sched_barrier(0);
;     }
;     lsum += ps + ps2;
;     pf[0] = fa::pack_p(p0, 0); pf[1] = fa::pack_p(p0, 8); pf[2] = fa::pack_p(p1, 0); pf[3] = fa::pack_p(p1, 8);
; }
.LBB0_1030:
	v_and_b32_e32 v35, 64, v1
	v_xor_b32_e32 v34, 32, v1
	v_add_u32_e32 v35, 64, v35
	v_cmp_lt_i32_e32 vcc, v34, v35
	v_max_f32_e32 v35, v191, v191
	s_nop 0
	v_cndmask_b32_e32 v34, v1, v34, vcc
	v_lshlrev_b32_e32 v34, 2, v34
	ds_bpermute_b32 v34, v34, v191
	s_waitcnt lgkmcnt(0)
	v_max_f32_e32 v34, v34, v34
	v_max_f32_e32 v35, v35, v34
	v_mov_b32_e32 v34, v35
	v_max_f32_e32 v36, 0, v34
	v_cndmask_b32_e64 v242, v36, v35, s[12:13]
	v_cndmask_b32_e64 v34, -v36, v212, s[12:13]
	v_exp_f32_e32 v34, v34
	v_add_f32_e32 v36, v190, v36
	v_cndmask_b32_e64 v190, v36, v35, s[12:13]
	v_mul_f32_e32 v66, v66, v34
	v_pk_mul_f32 v[128:129], v[128:129], v[34:35] op_sel_hi:[1,0]
	v_pk_mul_f32 v[126:127], v[126:127], v[34:35] op_sel_hi:[1,0]
	v_pk_mul_f32 v[124:125], v[124:125], v[34:35] op_sel_hi:[1,0]
	v_pk_mul_f32 v[122:123], v[122:123], v[34:35] op_sel_hi:[1,0]
	v_pk_mul_f32 v[120:121], v[120:121], v[34:35] op_sel_hi:[1,0]
	v_pk_mul_f32 v[118:119], v[118:119], v[34:35] op_sel_hi:[1,0]
	v_pk_mul_f32 v[116:117], v[116:117], v[34:35] op_sel_hi:[1,0]
	v_pk_mul_f32 v[114:115], v[114:115], v[34:35] op_sel_hi:[1,0]
	v_pk_mul_f32 v[112:113], v[112:113], v[34:35] op_sel_hi:[1,0]
	v_pk_mul_f32 v[110:111], v[110:111], v[34:35] op_sel_hi:[1,0]
	v_pk_mul_f32 v[108:109], v[108:109], v[34:35] op_sel_hi:[1,0]
	v_pk_mul_f32 v[106:107], v[106:107], v[34:35] op_sel_hi:[1,0]
	v_pk_mul_f32 v[104:105], v[104:105], v[34:35] op_sel_hi:[1,0]
	v_pk_mul_f32 v[102:103], v[102:103], v[34:35] op_sel_hi:[1,0]
	v_pk_mul_f32 v[100:101], v[100:101], v[34:35] op_sel_hi:[1,0]
	v_pk_mul_f32 v[98:99], v[98:99], v[34:35] op_sel_hi:[1,0]
	v_sub_f32_e32 v2, v2, v242
	v_sub_f32_e32 v3, v3, v242
	v_sub_f32_e32 v4, v4, v242
	v_sub_f32_e32 v5, v5, v242
	v_sub_f32_e32 v6, v6, v242
	v_sub_f32_e32 v7, v7, v242
	v_sub_f32_e32 v8, v8, v242
	v_sub_f32_e32 v9, v9, v242
	v_sub_f32_e32 v10, v10, v242
	v_sub_f32_e32 v11, v11, v242
	v_sub_f32_e32 v12, v12, v242
	v_sub_f32_e32 v13, v13, v242
	v_sub_f32_e32 v14, v14, v242
	v_sub_f32_e32 v15, v15, v242
	v_sub_f32_e32 v16, v16, v242
	v_sub_f32_e32 v17, v17, v242
	v_sub_f32_e32 v18, v18, v242
	v_sub_f32_e32 v19, v19, v242
	v_sub_f32_e32 v20, v20, v242
	v_sub_f32_e32 v21, v21, v242
	v_sub_f32_e32 v22, v22, v242
	v_sub_f32_e32 v23, v23, v242
	v_sub_f32_e32 v24, v24, v242
	v_sub_f32_e32 v25, v25, v242
	v_sub_f32_e32 v26, v26, v242
	v_sub_f32_e32 v27, v27, v242
	v_sub_f32_e32 v28, v28, v242
	v_sub_f32_e32 v29, v29, v242
	v_sub_f32_e32 v30, v30, v242
	v_sub_f32_e32 v31, v31, v242
	v_sub_f32_e32 v32, v32, v242
	v_sub_f32_e32 v33, v33, v242
	v_sub_f32_e32 v226, v226, v242
	v_sub_f32_e32 v227, v227, v242
	v_sub_f32_e32 v228, v228, v242
	v_sub_f32_e32 v229, v229, v242
	v_sub_f32_e32 v230, v230, v242
	v_sub_f32_e32 v231, v231, v242
	v_sub_f32_e32 v232, v232, v242
	v_sub_f32_e32 v233, v233, v242
	v_sub_f32_e32 v234, v234, v242
	v_sub_f32_e32 v235, v235, v242
	v_sub_f32_e32 v236, v236, v242
	v_sub_f32_e32 v237, v237, v242
	v_sub_f32_e32 v238, v238, v242
	v_sub_f32_e32 v239, v239, v242
	v_sub_f32_e32 v240, v240, v242
	v_sub_f32_e32 v241, v241, v242
.LBB0_1031:
	s_add_i32 s8, s8, 0
	v_add3_u32 v67, s8, v187, v180
	ds_read_b128 v[34:37], v67 offset:21504
	ds_read_b128 v[50:53], v67 offset:28160
	ds_read_b128 v[68:71], v67 offset:21536
	s_waitcnt lgkmcnt(1)
	v_mfma_f32_32x32x16_bf16 v[50:65], v[50:53], v[132:135], v[226:241]
	ds_read_b128 v[72:75], v67 offset:28192
	v_exp_f32_e32 v2, v2
	v_exp_f32_e32 v18, v18
	v_exp_f32_e32 v3, v3
	v_mfma_f32_32x32x16_bf16 v[34:49], v[34:37], v[132:135], v[226:241]
	v_exp_f32_e32 v19, v19
	s_waitcnt lgkmcnt(1)
	v_mfma_f32_32x32x16_bf16 v[34:49], v[68:71], v[136:139], v[34:49]
	ds_read_b128 v[76:79], v67 offset:21568
	ds_read_b128 v[80:83], v67 offset:28224
	s_waitcnt lgkmcnt(2)
	v_mfma_f32_32x32x16_bf16 v[50:65], v[72:75], v[136:139], v[50:65]
	v_exp_f32_e32 v4, v4
	v_exp_f32_e32 v20, v20
	v_exp_f32_e32 v5, v5
	v_exp_f32_e32 v21, v21
	v_exp_f32_e32 v6, v6
	v_exp_f32_e32 v22, v22
	v_exp_f32_e32 v7, v7
	v_exp_f32_e32 v23, v23
	s_waitcnt lgkmcnt(1)
	v_mfma_f32_32x32x16_bf16 v[34:49], v[76:79], v[140:143], v[34:49]
	ds_read_b128 v[68:71], v67 offset:21600
	ds_read_b128 v[72:75], v67 offset:28256
	v_exp_f32_e32 v8, v8
	s_waitcnt lgkmcnt(2)
	v_mfma_f32_32x32x16_bf16 v[50:65], v[80:83], v[140:143], v[50:65]
	v_exp_f32_e32 v24, v24
	v_exp_f32_e32 v9, v9
	v_exp_f32_e32 v25, v25
	s_waitcnt lgkmcnt(1)
	v_mfma_f32_32x32x16_bf16 v[34:49], v[68:71], v[144:147], v[34:49]
	ds_read_b128 v[76:79], v67 offset:21632
	ds_read_b128 v[80:83], v67 offset:28288
	v_exp_f32_e32 v10, v10
	s_waitcnt lgkmcnt(2)
	v_mfma_f32_32x32x16_bf16 v[50:65], v[72:75], v[144:147], v[50:65]
	v_exp_f32_e32 v26, v26
	v_exp_f32_e32 v11, v11
	v_exp_f32_e32 v27, v27
	s_waitcnt lgkmcnt(1)
	v_mfma_f32_32x32x16_bf16 v[34:49], v[76:79], v[148:151], v[34:49]
	ds_read_b128 v[68:71], v67 offset:21664
	ds_read_b128 v[72:75], v67 offset:28320
	s_waitcnt lgkmcnt(2)
	v_mfma_f32_32x32x16_bf16 v[50:65], v[80:83], v[148:151], v[50:65]
	v_exp_f32_e32 v12, v12
	v_exp_f32_e32 v28, v28
	v_exp_f32_e32 v13, v13
	v_exp_f32_e32 v29, v29
	v_exp_f32_e32 v14, v14
	v_exp_f32_e32 v30, v30
	v_exp_f32_e32 v15, v15
	v_exp_f32_e32 v31, v31
	v_add_f32_e32 v67, v18, v2
	v_add_f32_e32 v67, v67, v3
	v_add_f32_e32 v67, v19, v67
	v_add_f32_e32 v67, v67, v4
	v_add_f32_e32 v67, v20, v67
	v_add_f32_e32 v67, v67, v5
	v_add_f32_e32 v67, v21, v67
	v_add_f32_e32 v67, v67, v6
	v_add_f32_e32 v67, v22, v67
	v_add_f32_e32 v67, v67, v7
	v_add_f32_e32 v67, v23, v67
	v_add_f32_e32 v67, v67, v8
	v_add_f32_e32 v67, v24, v67
	v_add_f32_e32 v67, v67, v9
	v_add_f32_e32 v67, v25, v67
	v_add_f32_e32 v67, v67, v10
	v_add_f32_e32 v67, v26, v67
	v_add_f32_e32 v67, v67, v11
	v_add_f32_e32 v67, v27, v67
	v_add_f32_e32 v67, v67, v12
	v_add_f32_e32 v67, v28, v67
	v_add_f32_e32 v67, v67, v13
	v_add_f32_e32 v67, v29, v67
	v_exp_f32_e32 v16, v16
	s_waitcnt lgkmcnt(1)
; __device__ __forceinline__ void att_shift(float tm, bool first, float& mrun, float& lsum, fa::f32x16& o0, fa::f32x16& o1) {
;     if (first || __any(tm > mrun + 8.f)) {
;         tm = fmaxf(tm, __shfl_xor(tm, 32));
;         const float dl = first ? 0.f : fmaxf(tm - mrun, 0.f), alpha = __builtin_amdgcn_exp2f(-dl);
;         mrun = first ? tm : mrun + dl; lsum *= alpha;
; __device__ __forceinline__ void att_qk_exp(const LAS char* kb, const bf16x8 (&qf)[6], float nm, fa::f32x16& n0, fa::f32x16& n1, fa::f32x16& p0, fa::f32x16& p1, float& lsum, bf16x8 (&pf)[4]) {
;     ...
;     lsum += ps + ps2;
;     pf[0] = fa::pack_p(p0, 0); pf[1] = fa::pack_p(p0, 8); pf[2] = fa::pack_p(p1, 0); pf[3] = fa::pack_p(p1, 8);
; }
; __device__ __forceinline__ void att_exp_pack(fa::f32x16& p0, fa::f32x16& p1, float nm, float& lsum, bf16x8 (&pf)[4]) {
;     float ps = 0.f, ps2 = 0.f;
; #pragma unroll
;     for (int r = 0; r < 16; ++r) { p0[r] = __builtin_amdgcn_exp2f(vadd1(p0[r], nm)); p1[r] = __builtin_amdgcn_exp2f(vadd1(p1[r], nm)); ps += p0[r]; ps += p1[r]; }
;     lsum += ps + ps2;
;     pf[0] = fa::pack_p(p0, 0); pf[1] = fa::pack_p(p0, 8); pf[2] = fa::pack_p(p1, 0); pf[3] = fa::pack_p(p1, 8);
; }
; __device__ __forceinline__ float att_pv_max(fa::f32x16& o0, fa::f32x16& o1, const LAS char* vb, const bf16x8 (&pf)[4], const fa::f32x16& n0, const fa::f32x16& n1) {
;     using namespace fa;
;     float ta = n0[0], tb = n1[0];
;     s16x4 a0 = vtr(vb), a1 = vtr(vb + 512), b0 = vtr(vb + 4096), b1 = vtr(vb + 4096 + 512);
; #pragma unroll
;     for (int ks = 0; ks < 4; ++ks) {
;         s16x4 na0 = a0, na1 = a1, nb0 = b0, nb1 = b1;
;         if (ks < 3) { na0 = vtr(vb + (ks + 1) * 1024); na1 = vtr(vb + (ks + 1) * 1024 + 512); nb0 = vtr(vb + 4096 + (ks + 1) * 1024); nb1 = vtr(vb + 4096 + (ks + 1) * 1024 + 512); }
;         const bf16x8 v0 = (bf16x8){a0[0], a0[1], a0[2], a0[3], a1[0], a1[1], a1[2], a1[3]}, v1 = (bf16x8){b0[0], b0[1], b0[2], b0[3], b1[0], b1[1], b1[2], b1[3]};
;         o0 = __builtin_amdgcn_mfma_f32_32x32x16_bf16(v0, pf[ks], o0, 0, 0, 0);
;         o1 = __builtin_amdgcn_mfma_f32_32x32x16_bf16(v1, pf[ks], o1, 0, 0, 0);
; #pragma unroll
;         for (int r = 4 * ks; r < 4 * ks + 4; ++r) { ta = fmaxf(ta, n0[r]); tb = fmaxf(tb, n1[r]); }
;         a0 = na0; a1 = na1; b0 = nb0; b1 = nb1;
;         __builtin_amdgcn_sched_barrier(0);
;     }
;     return fmaxf(ta, tb);
; }
	v_mfma_f32_32x32x16_bf16 v[34:49], v[68:71], v[152:155], v[34:49]
	v_add_f32_e32 v67, v67, v14
	v_exp_f32_e32 v32, v32
	v_add_f32_e32 v67, v30, v67
	v_exp_f32_e32 v17, v17
	v_add_f32_e32 v67, v67, v15
	s_waitcnt lgkmcnt(0)
	v_mfma_f32_32x32x16_bf16 v[50:65], v[72:75], v[152:155], v[50:65]
	v_exp_f32_e32 v33, v33
	v_add_f32_e32 v67, v31, v67
	v_add_f32_e32 v67, v67, v16
	v_add_f32_e32 v67, v32, v67
	v_add_f32_e32 v67, v67, v17
	v_add_f32_e32 v67, v33, v67
	v_add_u32_e32 v193, s8, v189
	v_cvt_pk_bf16_f32 v68, v2, v3
	v_cvt_pk_bf16_f32 v69, v4, v5
	v_cvt_pk_bf16_f32 v70, v6, v7
	v_cvt_pk_bf16_f32 v71, v8, v9
	v_cvt_pk_bf16_f32 v72, v10, v11
	v_cvt_pk_bf16_f32 v73, v12, v13
	v_cvt_pk_bf16_f32 v74, v14, v15
	v_cvt_pk_bf16_f32 v75, v16, v17
	v_cvt_pk_bf16_f32 v76, v18, v19
	v_cvt_pk_bf16_f32 v77, v20, v21
	v_cvt_pk_bf16_f32 v78, v22, v23
	v_cvt_pk_bf16_f32 v79, v24, v25
	v_cvt_pk_bf16_f32 v196, v26, v27
	v_cvt_pk_bf16_f32 v197, v28, v29
	v_cvt_pk_bf16_f32 v198, v30, v31
	v_cvt_pk_bf16_f32 v199, v32, v33
	ds_read_b64_tr_b16 v[80:81], v193 offset:13312
	ds_read_b64_tr_b16 v[82:83], v193 offset:13824
	ds_read_b64_tr_b16 v[84:85], v193 offset:14336
	ds_read_b64_tr_b16 v[86:87], v193 offset:14848
	s_waitcnt lgkmcnt(2)
	v_mfma_f32_32x32x16_bf16 v[114:129], v[80:83], v[68:71], v[114:129]
	ds_read_b64_tr_b16 v[80:81], v193 offset:17408
	ds_read_b64_tr_b16 v[82:83], v193 offset:17920
	ds_read_b64_tr_b16 v[88:89], v193 offset:18432
	ds_read_b64_tr_b16 v[90:91], v193 offset:18944
	v_add_f32_e32 v192, v66, v67
	s_waitcnt lgkmcnt(2)
	v_mfma_f32_32x32x16_bf16 v[98:113], v[80:83], v[68:71], v[98:113]
	s_waitcnt lgkmcnt(0)
	v_mfma_f32_32x32x16_bf16 v[98:113], v[88:91], v[72:75], v[98:113]
	ds_read_b64_tr_b16 v[66:67], v193 offset:15360
	ds_read_b64_tr_b16 v[68:69], v193 offset:15872
	ds_read_b64_tr_b16 v[80:81], v193 offset:19456
	ds_read_b64_tr_b16 v[82:83], v193 offset:19968
	v_mfma_f32_32x32x16_bf16 v[114:129], v[84:87], v[72:75], v[114:129]
	s_waitcnt lgkmcnt(0)
	v_mfma_f32_32x32x16_bf16 v[98:113], v[80:83], v[76:79], v[98:113]
	ds_read_b64_tr_b16 v[84:85], v193 offset:16384
	ds_read_b64_tr_b16 v[86:87], v193 offset:16896
	ds_read_b64_tr_b16 v[200:201], v193 offset:20480
	ds_read_b64_tr_b16 v[202:203], v193 offset:20992
	v_mfma_f32_32x32x16_bf16 v[114:129], v[66:69], v[76:79], v[114:129]
	v_max_f32_e32 v66, v51, v51
	v_max_f32_e32 v67, v50, v50
	v_max_f32_e32 v66, v67, v66
	v_max3_f32 v66, v66, v52, v53
	v_max3_f32 v66, v66, v54, v55
	v_max3_f32 v66, v66, v56, v57
	v_max3_f32 v82, v66, v58, v59
	v_max3_f32 v66, v82, v60, v61
	v_max3_f32 v82, v34, v35, v36
	v_max3_f32 v82, v82, v37, v38
	v_max3_f32 v82, v82, v39, v40
	v_max3_f32 v82, v82, v41, v42
	s_waitcnt lgkmcnt(2)
	v_mfma_f32_32x32x16_bf16 v[114:129], v[84:87], v[196:199], v[114:129]
	v_max3_f32 v67, v82, v43, v44
	v_max3_f32 v82, v67, v45, v46
	v_max3_f32 v83, v66, v62, v63
	s_waitcnt lgkmcnt(0)
	v_mfma_f32_32x32x16_bf16 v[98:113], v[200:203], v[196:199], v[98:113]
	v_max3_f32 v82, v82, v47, v48
	v_max3_f32 v83, v83, v64, v65
	v_max3_f32 v82, v82, v49, v83
	v_cmp_lt_f32_e32 vcc, 0x41000000, v82
	s_cbranch_vccz .LBB0_1033
	v_and_b32_e32 v84, 64, v1
	v_xor_b32_e32 v83, 32, v1
	v_add_u32_e32 v84, 64, v84
	v_cmp_lt_i32_e32 vcc, v83, v84
	s_nop 1
	v_cndmask_b32_e32 v83, v1, v83, vcc
	v_lshlrev_b32_e32 v83, 2, v83
	ds_bpermute_b32 v83, v83, v82
	v_max_f32_e32 v82, v82, v82
	s_waitcnt lgkmcnt(0)
	v_max_f32_e32 v83, v83, v83
	v_max_f32_e32 v82, v82, v83
	v_max_f32_e32 v83, 0, v82
	v_exp_f32_e64 v82, -v83
	v_add_f32_e32 v190, v190, v83
	v_mul_f32_e32 v192, v192, v82
	v_pk_mul_f32 v[128:129], v[128:129], v[82:83] op_sel_hi:[1,0]
	v_pk_mul_f32 v[126:127], v[126:127], v[82:83] op_sel_hi:[1,0]
	v_pk_mul_f32 v[124:125], v[124:125], v[82:83] op_sel_hi:[1,0]
	v_pk_mul_f32 v[122:123], v[122:123], v[82:83] op_sel_hi:[1,0]
	v_pk_mul_f32 v[120:121], v[120:121], v[82:83] op_sel_hi:[1,0]
	v_pk_mul_f32 v[118:119], v[118:119], v[82:83] op_sel_hi:[1,0]
	v_pk_mul_f32 v[116:117], v[116:117], v[82:83] op_sel_hi:[1,0]
	v_pk_mul_f32 v[114:115], v[114:115], v[82:83] op_sel_hi:[1,0]
	v_pk_mul_f32 v[112:113], v[112:113], v[82:83] op_sel_hi:[1,0]
	v_pk_mul_f32 v[110:111], v[110:111], v[82:83] op_sel_hi:[1,0]
	v_pk_mul_f32 v[108:109], v[108:109], v[82:83] op_sel_hi:[1,0]
	v_pk_mul_f32 v[106:107], v[106:107], v[82:83] op_sel_hi:[1,0]
	v_pk_mul_f32 v[104:105], v[104:105], v[82:83] op_sel_hi:[1,0]
	v_pk_mul_f32 v[102:103], v[102:103], v[82:83] op_sel_hi:[1,0]
	v_pk_mul_f32 v[100:101], v[100:101], v[82:83] op_sel_hi:[1,0]
	v_pk_mul_f32 v[98:99], v[98:99], v[82:83] op_sel_hi:[1,0]
	v_sub_f32_e32 v34, v34, v83
	v_sub_f32_e32 v35, v35, v83
	v_sub_f32_e32 v36, v36, v83
	v_sub_f32_e32 v37, v37, v83
	v_sub_f32_e32 v38, v38, v83
	v_sub_f32_e32 v39, v39, v83
	v_sub_f32_e32 v40, v40, v83
	v_sub_f32_e32 v41, v41, v83
	v_sub_f32_e32 v42, v42, v83
	v_sub_f32_e32 v43, v43, v83
	v_sub_f32_e32 v44, v44, v83
	v_sub_f32_e32 v45, v45, v83
	v_sub_f32_e32 v46, v46, v83
	v_sub_f32_e32 v47, v47, v83
	v_sub_f32_e32 v48, v48, v83
	v_sub_f32_e32 v49, v49, v83
	v_sub_f32_e32 v50, v50, v83
	v_sub_f32_e32 v51, v51, v83
	v_sub_f32_e32 v52, v52, v83
	v_sub_f32_e32 v53, v53, v83
	v_sub_f32_e32 v54, v54, v83
	v_sub_f32_e32 v55, v55, v83
	v_sub_f32_e32 v56, v56, v83
	v_sub_f32_e32 v57, v57, v83
	v_sub_f32_e32 v58, v58, v83
	v_sub_f32_e32 v59, v59, v83
	v_sub_f32_e32 v60, v60, v83
	v_sub_f32_e32 v61, v61, v83
	v_sub_f32_e32 v62, v62, v83
	v_sub_f32_e32 v63, v63, v83
	v_sub_f32_e32 v64, v64, v83
	v_sub_f32_e32 v65, v65, v83
	v_sub_f32_e32 v226, v226, v83
	v_sub_f32_e32 v227, v227, v83
	v_sub_f32_e32 v228, v228, v83
	v_sub_f32_e32 v229, v229, v83
	v_sub_f32_e32 v230, v230, v83
	v_sub_f32_e32 v231, v231, v83
	v_sub_f32_e32 v232, v232, v83
	v_sub_f32_e32 v233, v233, v83
	v_sub_f32_e32 v234, v234, v83
	v_sub_f32_e32 v235, v235, v83
	v_sub_f32_e32 v236, v236, v83
	v_sub_f32_e32 v237, v237, v83
	v_sub_f32_e32 v238, v238, v83
	v_sub_f32_e32 v239, v239, v83
	v_sub_f32_e32 v240, v240, v83
	v_sub_f32_e32 v241, v241, v83
; __device__ __forceinline__ bf16x8 pack_p(const f32x16& p, int base) { u32x4 w; w.x = pk2(p[base], p[base + 1]); w.y = pk2(p[base + 2], p[base + 3]); w.z = pk2(p[base + 4], p[base + 5]); w.w = pk2(p[base + 6], p[base + 7]); return __builtin_bit_cast(bf16x8, w); }
; __device__ __forceinline__ float vadd1(float a, float b) { float r; asm("v_add_f32 %0, %1, %2" : "=v"(r) : "v"(a), "v"(b)); return r; }
; __device__ __forceinline__ void att_exp_pack(fa::f32x16& p0, fa::f32x16& p1, float nm, float& lsum, bf16x8 (&pf)[4]) {
;     float ps = 0.f, ps2 = 0.f;
; #pragma unroll
;     for (int r = 0; r < 16; ++r) { p0[r] = __builtin_amdgcn_exp2f(vadd1(p0[r], nm)); p1[r] = __builtin_amdgcn_exp2f(vadd1(p1[r], nm)); ps += p0[r]; ps += p1[r]; }
;     lsum += ps + ps2;
;     pf[0] = fa::pack_p(p0, 0); pf[1] = fa::pack_p(p0, 8); pf[2] = fa::pack_p(p1, 0); pf[3] = fa::pack_p(p1, 8);
; }
; __device__ __forceinline__ void ph_attn_mfma(unsigned char* lds_, const bf16_t* Q, const bf16_t* Kb, const bf16_t* Vb, bf16_t* Z, int with_ctx, int u0, int ustep) { PH_IDS;
;     ...
;             __syncthreads();
;             if (more) {
;                 att_qk_exp(sm + nxt + r32 * KP_A + 16 * hi, qf, -mrun, a0, a1, b0, b1, lsum, pf);
;                 tmA = att_pv_max(o0, o1, sm + cur + BUF_A + vrd, pf, a0, a1);
;             } else {
;                 att_exp_pack(b0, b1, -mrun, lsum, pf);
;                 pv_tile(o0, o1, sm + cur + BUF_A + vrd, pf);
.LBB0_1033:
	s_mov_b64 s[8:9], -1
	s_and_b64 vcc, exec, s[10:11]
	s_barrier
	s_cbranch_vccz .LBB0_1035
	v_exp_f32_e32 v82, v34
	v_exp_f32_e32 v83, v50
	v_exp_f32_e32 v85, v35
	v_exp_f32_e32 v86, v51
	v_add_f32_e32 v84, 0, v82
	v_exp_f32_e32 v87, v36
	v_add_f32_e32 v84, v83, v84
	v_exp_f32_e32 v88, v52
	v_add_f32_e32 v84, v84, v85
	v_exp_f32_e32 v89, v37
	v_add_f32_e32 v84, v86, v84
	v_exp_f32_e32 v90, v53
	v_add_f32_e32 v84, v84, v87
	v_exp_f32_e32 v91, v38
	v_add_f32_e32 v84, v88, v84
	v_exp_f32_e32 v92, v54
	v_add_f32_e32 v84, v84, v89
	v_exp_f32_e32 v93, v39
	v_add_f32_e32 v84, v90, v84
	v_exp_f32_e32 v94, v55
	v_add_f32_e32 v84, v84, v91
	v_exp_f32_e32 v95, v40
	v_add_f32_e32 v84, v92, v84
	v_exp_f32_e32 v96, v56
	v_add_f32_e32 v84, v84, v93
	v_exp_f32_e32 v97, v41
	v_add_f32_e32 v84, v94, v84
	v_exp_f32_e32 v66, v57
	v_add_f32_e32 v84, v84, v95
	v_exp_f32_e32 v67, v42
	v_add_f32_e32 v84, v96, v84
	v_exp_f32_e32 v68, v58
	v_add_f32_e32 v84, v84, v97
	v_exp_f32_e32 v69, v43
	v_add_f32_e32 v84, v66, v84
	v_exp_f32_e32 v70, v59
	v_add_f32_e32 v84, v84, v67
	v_exp_f32_e32 v71, v44
	v_add_f32_e32 v84, v68, v84
	v_exp_f32_e32 v72, v60
	v_add_f32_e32 v84, v84, v69
	v_exp_f32_e32 v73, v45
	v_add_f32_e32 v84, v70, v84
	v_exp_f32_e32 v74, v61
	v_add_f32_e32 v84, v84, v71
	v_exp_f32_e32 v75, v46
	v_add_f32_e32 v84, v72, v84
	v_exp_f32_e32 v76, v62
	v_add_f32_e32 v84, v84, v73
	v_exp_f32_e32 v77, v47
	v_add_f32_e32 v84, v74, v84
	v_exp_f32_e32 v78, v63
	v_add_f32_e32 v84, v84, v75
	v_exp_f32_e32 v79, v48
	v_add_f32_e32 v84, v76, v84
	v_exp_f32_e32 v80, v64
	v_add_f32_e32 v84, v84, v77
	v_exp_f32_e32 v81, v49
	v_add_f32_e32 v84, v78, v84
	v_add_f32_e32 v84, v84, v79
	v_exp_f32_e32 v204, v65
	v_add_f32_e32 v84, v80, v84
	v_add_f32_e32 v84, v84, v81
	v_cvt_pk_bf16_f32 v196, v82, v85
	v_add_f32_e32 v195, v204, v84
	v_cvt_pk_bf16_f32 v197, v87, v89
	v_cvt_pk_bf16_f32 v198, v91, v93
	v_cvt_pk_bf16_f32 v199, v95, v97
	v_cvt_pk_bf16_f32 v200, v67, v69
	v_cvt_pk_bf16_f32 v201, v71, v73
	v_cvt_pk_bf16_f32 v202, v75, v77
	v_cvt_pk_bf16_f32 v203, v79, v81
	v_cvt_pk_bf16_f32 v214, v83, v86
	v_cvt_pk_bf16_f32 v215, v88, v90
	v_cvt_pk_bf16_f32 v216, v92, v94
	v_cvt_pk_bf16_f32 v217, v96, v66
	v_cvt_pk_bf16_f32 v218, v68, v70
	v_cvt_pk_bf16_f32 v219, v72, v74
	v_cvt_pk_bf16_f32 v220, v76, v78
	v_cvt_pk_bf16_f32 v221, v80, v204
	ds_read_b64_tr_b16 v[82:83], v193 offset:34816
	ds_read_b64_tr_b16 v[84:85], v193 offset:35328
	ds_read_b64_tr_b16 v[222:223], v193 offset:38912
	ds_read_b64_tr_b16 v[224:225], v193 offset:39424
	s_waitcnt lgkmcnt(2)
	v_mfma_f32_32x32x16_bf16 v[114:129], v[82:85], v[196:199], v[114:129]
	s_mov_b64 s[8:9], 0
	s_waitcnt lgkmcnt(0)
	v_mfma_f32_32x32x16_bf16 v[98:113], v[222:225], v[196:199], v[98:113]
	ds_read_b64_tr_b16 v[196:197], v193 offset:35840
	ds_read_b64_tr_b16 v[198:199], v193 offset:36352
	ds_read_b64_tr_b16 v[222:223], v193 offset:39936
	ds_read_b64_tr_b16 v[224:225], v193 offset:40448
	s_waitcnt lgkmcnt(2)
	v_mfma_f32_32x32x16_bf16 v[114:129], v[196:199], v[200:203], v[114:129]
	s_waitcnt lgkmcnt(0)
	v_mfma_f32_32x32x16_bf16 v[98:113], v[222:225], v[200:203], v[98:113]
	ds_read_b64_tr_b16 v[196:197], v193 offset:36864
	ds_read_b64_tr_b16 v[198:199], v193 offset:37376
	ds_read_b64_tr_b16 v[200:201], v193 offset:40960
	ds_read_b64_tr_b16 v[202:203], v193 offset:41472
	s_waitcnt lgkmcnt(2)
	v_mfma_f32_32x32x16_bf16 v[114:129], v[196:199], v[214:217], v[114:129]
	s_waitcnt lgkmcnt(0)
	v_mfma_f32_32x32x16_bf16 v[98:113], v[200:203], v[214:217], v[98:113]
	ds_read_b64_tr_b16 v[196:197], v193 offset:37888
	ds_read_b64_tr_b16 v[198:199], v193 offset:38400
	ds_read_b64_tr_b16 v[200:201], v193 offset:41984
	ds_read_b64_tr_b16 v[202:203], v193 offset:42496
	s_waitcnt lgkmcnt(2)
	v_mfma_f32_32x32x16_bf16 v[114:129], v[196:199], v[218:221], v[114:129]
	s_waitcnt lgkmcnt(0)
	v_mfma_f32_32x32x16_bf16 v[98:113], v[200:203], v[218:221], v[98:113]
; #define LAS __attribute__((address_space(3)))
; __device__ __forceinline__ void att_qk_exp(const LAS char* kb, const bf16x8 (&qf)[6], float nm, fa::f32x16& n0, fa::f32x16& n1, fa::f32x16& p0, fa::f32x16& p1, float& lsum, bf16x8 (&pf)[4]) {
;     const fa::f32x16 zero = {0.f, 0.f, 0.f, 0.f, 0.f, 0.f, 0.f, 0.f, 0.f, 0.f, 0.f, 0.f, 0.f, 0.f, 0.f, 0.f};
;     bf16x8 kc0 = *(const LAS bf16x8*)kb, kc1 = *(const LAS bf16x8*)(kb + 32 * fa::KP_A);
;     float ps = 0.f, ps2 = 0.f;
; #pragma unroll
;     for (int st = 0; st < 6; ++st) {
;         bf16x8 kn0 = kc0, kn1 = kc1;
;         if (st < 5) { kn0 = *(const LAS bf16x8*)(kb + 32 * (st + 1)); kn1 = *(const LAS bf16x8*)(kb + 32 * fa::KP_A + 32 * (st + 1)); }
;         n0 = __builtin_amdgcn_mfma_f32_32x32x16_bf16(kc0, qf[st], st == 0 ? zero : n0, 0, 0, 0);
;         n1 = __builtin_amdgcn_mfma_f32_32x32x16_bf16(kc1, qf[st], st == 0 ? zero : n1, 0, 0, 0);
;         constexpr int lo[7] = {0, 2, 6, 8, 10, 14, 16};
; #pragma unroll
;         for (int r = lo[st]; r < lo[st + 1]; ++r) {
;             p0[r] = __builtin_amdgcn_exp2f(vadd1(p0[r], nm)); p1[r] = __builtin_amdgcn_exp2f(vadd1(p1[r], nm));
;             ps += p0[r]; ps += p1[r]; }
;         kc0 = kn0; kc1 = kn1;
;         __builtin_amdgcn_sched_barrier(0);
;     }
;     lsum += ps + ps2;
;     pf[0] = fa::pack_p(p0, 0); pf[1] = fa::pack_p(p0, 8); pf[2] = fa::pack_p(p1, 0); pf[3] = fa::pack_p(p1, 8);
; }
; __device__ __forceinline__ void att_exp_pack(fa::f32x16& p0, fa::f32x16& p1, float nm, float& lsum, bf16x8 (&pf)[4]) {
;     float ps = 0.f, ps2 = 0.f;
; #pragma unroll
;     for (int r = 0; r < 16; ++r) { p0[r] = __builtin_amdgcn_exp2f(vadd1(p0[r], nm)); p1[r] = __builtin_amdgcn_exp2f(vadd1(p1[r], nm)); ps += p0[r]; ps += p1[r]; }
;     lsum += ps + ps2;
;     pf[0] = fa::pack_p(p0, 0); pf[1] = fa::pack_p(p0, 8); pf[2] = fa::pack_p(p1, 0); pf[3] = fa::pack_p(p1, 8);
; }
; __device__ __forceinline__ float att_pv_max(fa::f32x16& o0, fa::f32x16& o1, const LAS char* vb, const bf16x8 (&pf)[4], const fa::f32x16& n0, const fa::f32x16& n1) {
;     using namespace fa;
;     float ta = n0[0], tb = n1[0];
;     s16x4 a0 = vtr(vb), a1 = vtr(vb + 512), b0 = vtr(vb + 4096), b1 = vtr(vb + 4096 + 512);
; #pragma unroll
;     for (int ks = 0; ks < 4; ++ks) {
;         s16x4 na0 = a0, na1 = a1, nb0 = b0, nb1 = b1;
.LBB0_1035:
	s_andn2_b64 vcc, exec, s[8:9]
	s_cbranch_vccnz .LBB0_1037
	v_add_u32_e32 v66, s18, v188
	ds_read_b128 v[2:5], v66
	ds_read_b128 v[18:21], v66 offset:6656
	ds_read_b128 v[82:85], v66 offset:32
	ds_read_b128 v[86:89], v66 offset:6688
	v_exp_f32_e32 v67, v34
	v_exp_f32_e32 v68, v50
	s_waitcnt lgkmcnt(3)
	v_mfma_f32_32x32x16_bf16 v[2:17], v[2:5], v[132:135], v[226:241]
	v_exp_f32_e32 v69, v35
	v_exp_f32_e32 v70, v51
	s_waitcnt lgkmcnt(2)
	v_mfma_f32_32x32x16_bf16 v[18:33], v[18:21], v[132:135], v[226:241]
	s_waitcnt lgkmcnt(1)
	v_mfma_f32_32x32x16_bf16 v[2:17], v[82:85], v[136:139], v[2:17]
	v_exp_f32_e32 v71, v36
	ds_read_b128 v[90:93], v66 offset:64
	ds_read_b128 v[94:97], v66 offset:6720
	v_exp_f32_e32 v72, v52
	v_exp_f32_e32 v82, v37
	s_waitcnt lgkmcnt(2)
	v_mfma_f32_32x32x16_bf16 v[18:33], v[86:89], v[136:139], v[18:33]
	v_exp_f32_e32 v83, v53
	v_exp_f32_e32 v84, v38
	v_exp_f32_e32 v85, v54
	v_exp_f32_e32 v73, v39
	v_exp_f32_e32 v74, v55
	s_waitcnt lgkmcnt(1)
	v_mfma_f32_32x32x16_bf16 v[2:17], v[90:93], v[140:143], v[2:17]
	ds_read_b128 v[34:37], v66 offset:96
	ds_read_b128 v[50:53], v66 offset:6752
	v_exp_f32_e32 v86, v40
	v_exp_f32_e32 v87, v56
	s_waitcnt lgkmcnt(2)
	v_mfma_f32_32x32x16_bf16 v[18:33], v[94:97], v[140:143], v[18:33]
	v_exp_f32_e32 v88, v41
	v_exp_f32_e32 v89, v57
	s_waitcnt lgkmcnt(1)
	v_mfma_f32_32x32x16_bf16 v[2:17], v[34:37], v[144:147], v[2:17]
	ds_read_b128 v[38:41], v66 offset:128
	ds_read_b128 v[54:57], v66 offset:6784
	v_exp_f32_e32 v42, v42
	v_exp_f32_e32 v58, v58
	s_waitcnt lgkmcnt(2)
	v_mfma_f32_32x32x16_bf16 v[18:33], v[50:53], v[144:147], v[18:33]
	v_exp_f32_e32 v43, v43
	v_exp_f32_e32 v59, v59
	s_waitcnt lgkmcnt(1)
	v_mfma_f32_32x32x16_bf16 v[2:17], v[38:41], v[148:151], v[2:17]
	ds_read_b128 v[34:37], v66 offset:160
	ds_read_b128 v[50:53], v66 offset:6816
	v_exp_f32_e32 v39, v45
	s_waitcnt lgkmcnt(2)
	v_mfma_f32_32x32x16_bf16 v[18:33], v[54:57], v[148:151], v[18:33]
	v_exp_f32_e32 v61, v61
	v_exp_f32_e32 v44, v44
	v_exp_f32_e32 v40, v46
	v_exp_f32_e32 v60, v60
	v_exp_f32_e32 v62, v62
	v_exp_f32_e32 v41, v47
	v_exp_f32_e32 v63, v63
	s_waitcnt lgkmcnt(1)
	v_mfma_f32_32x32x16_bf16 v[2:17], v[34:37], v[152:155], v[2:17]
	v_exp_f32_e32 v45, v48
	v_exp_f32_e32 v54, v64
	v_mov_b32_e32 v38, v49
	v_exp_f32_e32 v49, v65
	v_add_f32_e32 v34, v68, v67
	v_add_f32_e32 v34, v34, v69
	v_add_f32_e32 v34, v70, v34
	v_add_f32_e32 v34, v34, v71
	v_add_f32_e32 v34, v72, v34
	v_add_f32_e32 v34, v34, v82
	v_add_f32_e32 v34, v83, v34
	v_add_f32_e32 v34, v34, v84
	v_add_f32_e32 v34, v85, v34
	v_add_f32_e32 v34, v34, v73
	v_add_f32_e32 v34, v74, v34
	v_add_f32_e32 v34, v34, v86
	v_add_f32_e32 v34, v87, v34
	v_add_f32_e32 v34, v34, v88
	v_add_f32_e32 v34, v89, v34
	v_add_f32_e32 v34, v34, v42
	v_add_f32_e32 v34, v58, v34
	v_add_f32_e32 v34, v34, v43
	v_add_f32_e32 v34, v59, v34
	v_add_f32_e32 v34, v34, v44
	v_add_f32_e32 v34, v60, v34
	v_add_f32_e32 v34, v34, v39
	v_add_f32_e32 v34, v61, v34
	s_waitcnt lgkmcnt(0)
	v_mfma_f32_32x32x16_bf16 v[18:33], v[50:53], v[152:155], v[18:33]
	v_add_f32_e32 v34, v34, v40
	v_add_f32_e32 v34, v62, v34
	v_exp_f32_e32 v46, v38
	v_add_f32_e32 v34, v34, v41
	v_add_f32_e32 v34, v63, v34
	v_add_f32_e32 v34, v34, v45
	v_add_f32_e32 v34, v54, v34
	v_add_f32_e32 v34, v34, v46
	v_add_f32_e32 v195, v49, v34
	v_cvt_pk_bf16_f32 v34, v67, v69
	v_cvt_pk_bf16_f32 v35, v71, v82
	v_cvt_pk_bf16_f32 v36, v84, v73
	v_cvt_pk_bf16_f32 v37, v86, v88
	v_cvt_pk_bf16_f32 v38, v42, v43
	v_cvt_pk_bf16_f32 v39, v44, v39
	v_cvt_pk_bf16_f32 v40, v40, v41
	v_cvt_pk_bf16_f32 v41, v45, v46
	v_cvt_pk_bf16_f32 v42, v68, v70
	v_cvt_pk_bf16_f32 v43, v72, v83
	v_cvt_pk_bf16_f32 v44, v85, v74
	v_cvt_pk_bf16_f32 v45, v87, v89
	v_cvt_pk_bf16_f32 v46, v58, v59
	v_cvt_pk_bf16_f32 v47, v60, v61
	v_cvt_pk_bf16_f32 v48, v62, v63
	v_cvt_pk_bf16_f32 v49, v54, v49
	ds_read_b64_tr_b16 v[50:51], v193 offset:34816
	ds_read_b64_tr_b16 v[52:53], v193 offset:35328
	ds_read_b64_tr_b16 v[54:55], v193 offset:35840
	ds_read_b64_tr_b16 v[56:57], v193 offset:36352
	s_waitcnt lgkmcnt(2)
	v_mfma_f32_32x32x16_bf16 v[114:129], v[50:53], v[34:37], v[114:129]
	ds_read_b64_tr_b16 v[50:51], v193 offset:38912
	ds_read_b64_tr_b16 v[52:53], v193 offset:39424
	ds_read_b64_tr_b16 v[58:59], v193 offset:39936
	ds_read_b64_tr_b16 v[60:61], v193 offset:40448
	s_waitcnt lgkmcnt(2)
	v_mfma_f32_32x32x16_bf16 v[98:113], v[50:53], v[34:37], v[98:113]
	ds_read_b64_tr_b16 v[34:35], v193 offset:36864
	ds_read_b64_tr_b16 v[36:37], v193 offset:37376
	ds_read_b64_tr_b16 v[50:51], v193 offset:40960
	ds_read_b64_tr_b16 v[52:53], v193 offset:41472
	v_mfma_f32_32x32x16_bf16 v[114:129], v[54:57], v[38:41], v[114:129]
	s_waitcnt lgkmcnt(4)
	v_mfma_f32_32x32x16_bf16 v[98:113], v[58:61], v[38:41], v[98:113]
	s_waitcnt lgkmcnt(2)
	v_mfma_f32_32x32x16_bf16 v[114:129], v[34:37], v[42:45], v[114:129]
	ds_read_b64_tr_b16 v[34:35], v193 offset:37888
	ds_read_b64_tr_b16 v[36:37], v193 offset:38400
	ds_read_b64_tr_b16 v[38:39], v193 offset:41984
	ds_read_b64_tr_b16 v[40:41], v193 offset:42496
	s_waitcnt lgkmcnt(4)
	v_mfma_f32_32x32x16_bf16 v[98:113], v[50:53], v[42:45], v[98:113]
	v_max_f32_e32 v42, v19, v19
	v_max_f32_e32 v43, v18, v18
	v_max_f32_e32 v42, v43, v42
	v_max3_f32 v42, v42, v20, v21
	s_waitcnt lgkmcnt(2)
	v_mfma_f32_32x32x16_bf16 v[114:129], v[34:37], v[46:49], v[114:129]
	v_max3_f32 v35, v2, v3, v4
	v_max3_f32 v42, v42, v22, v23
	v_max3_f32 v35, v35, v5, v6
	v_max3_f32 v42, v42, v24, v25
	v_max3_f32 v35, v35, v7, v8
	v_max3_f32 v34, v42, v26, v27
	v_max3_f32 v35, v35, v9, v10
	v_max3_f32 v34, v34, v28, v29
	v_max3_f32 v35, v35, v11, v12
	v_max3_f32 v35, v35, v13, v14
	v_max3_f32 v34, v34, v30, v31
	s_waitcnt lgkmcnt(0)
	v_mfma_f32_32x32x16_bf16 v[98:113], v[38:41], v[46:49], v[98:113]
	v_max3_f32 v35, v35, v15, v16
	v_max3_f32 v34, v34, v32, v33
	v_max3_f32 v191, v35, v17, v34

; #define LAS __attribute__((address_space(3)))
; __device__ __forceinline__ float vadd1(float a, float b) { float r; asm("v_add_f32 %0, %1, %2" : "=v"(r) : "v"(a), "v"(b)); return r; }
; __device__ __forceinline__ void att_shift(float tm, bool first, float& mrun, float& lsum, fa::f32x16& o0, fa::f32x16& o1) {
;     if (first || __any(tm > mrun + 8.f)) {
;         tm = fmaxf(tm, __shfl_xor(tm, 32));
;         const float dl = first ? 0.f : fmaxf(tm - mrun, 0.f), alpha = __builtin_amdgcn_exp2f(-dl);
;         mrun = first ? tm : mrun + dl; lsum *= alpha;
; #pragma unroll
;         for (int r = 0; r < 16; ++r) { o0[r] *= alpha; o1[r] *= alpha; }
;     }
; }
; __device__ __forceinline__ void att_qk_exp(const LAS char* kb, const bf16x8 (&qf)[6], float nm, fa::f32x16& n0, fa::f32x16& n1, fa::f32x16& p0, fa::f32x16& p1, float& lsum, bf16x8 (&pf)[4]) {
;     const fa::f32x16 zero = {0.f, 0.f, 0.f, 0.f, 0.f, 0.f, 0.f, 0.f, 0.f, 0.f, 0.f, 0.f, 0.f, 0.f, 0.f, 0.f};
;     bf16x8 kc0 = *(const LAS bf16x8*)kb, kc1 = *(const LAS bf16x8*)(kb + 32 * fa::KP_A);
;     float ps = 0.f, ps2 = 0.f;
; #pragma unroll
;     for (int st = 0; st < 6; ++st) {
;         bf16x8 kn0 = kc0, kn1 = kc1;
;         if (st < 5) { kn0 = *(const LAS bf16x8*)(kb + 32 * (st + 1)); kn1 = *(const LAS bf16x8*)(kb + 32 * fa::KP_A + 32 * (st + 1)); }
;         n0 = __builtin_amdgcn_mfma_f32_32x32x16_bf16(kc0, qf[st], st == 0 ? zero : n0, 0, 0, 0);
;         n1 = __builtin_amdgcn_mfma_f32_32x32x16_bf16(kc1, qf[st], st == 0 ? zero : n1, 0, 0, 0);
;         constexpr int lo[7] = {0, 2, 6, 8, 10, 14, 16};
; #pragma unroll
;         for (int r = lo[st]; r < lo[st + 1]; ++r) {
;             p0[r] = __builtin_amdgcn_exp2f(vadd1(p0[r], nm)); p1[r] = __builtin_amdgcn_exp2f(vadd1(p1[r], nm));
;             ps += p0[r]; ps += p1[r]; }
;         kc0 = kn0; kc1 = kn1;
;         __builtin_amdgcn_sched_barrier(0);
;     }
.LBB0_2987:
	s_cmp_eq_u32 s10, 0
	s_cselect_b64 s[14:15], -1, 0
	s_and_b64 vcc, exec, s[14:15]
	s_mov_b64 s[16:17], s[14:15]
	s_cbranch_vccnz .LBB0_2989
	v_cmp_lt_f32_e32 vcc, 0x41000000, v201
	s_cmp_lg_u64 vcc, 0
	s_cselect_b64 s[16:17], -1, 0
.LBB0_2989:
	s_andn2_b64 vcc, exec, s[16:17]
	s_cbranch_vccnz .LBB0_2991
	v_and_b32_e32 v35, 64, v1
	v_xor_b32_e32 v34, 32, v1
	v_add_u32_e32 v35, 64, v35
	v_cmp_lt_i32_e32 vcc, v34, v35
	v_max_f32_e32 v35, v201, v201
	s_nop 0
	v_cndmask_b32_e32 v34, v1, v34, vcc
	v_lshlrev_b32_e32 v34, 2, v34
	ds_bpermute_b32 v34, v34, v201
	s_waitcnt lgkmcnt(0)
	v_max_f32_e32 v34, v34, v34
	v_max_f32_e32 v35, v35, v34
	v_mov_b32_e32 v34, v35
	v_max_f32_e32 v36, 0, v34
	v_cndmask_b32_e64 v248, v36, v35, s[14:15]
	v_cndmask_b32_e64 v34, -v36, v213, s[14:15]
	v_exp_f32_e32 v34, v34
	v_add_f32_e32 v36, v131, v36
	v_cndmask_b32_e64 v131, v36, v35, s[14:15]
	v_mul_f32_e32 v98, v98, v34
	v_pk_mul_f32 v[96:97], v[96:97], v[34:35] op_sel_hi:[1,0]
	v_pk_mul_f32 v[94:95], v[94:95], v[34:35] op_sel_hi:[1,0]
	v_pk_mul_f32 v[92:93], v[92:93], v[34:35] op_sel_hi:[1,0]
	v_pk_mul_f32 v[90:91], v[90:91], v[34:35] op_sel_hi:[1,0]
	v_pk_mul_f32 v[88:89], v[88:89], v[34:35] op_sel_hi:[1,0]
	v_pk_mul_f32 v[86:87], v[86:87], v[34:35] op_sel_hi:[1,0]
	v_pk_mul_f32 v[84:85], v[84:85], v[34:35] op_sel_hi:[1,0]
	v_pk_mul_f32 v[82:83], v[82:83], v[34:35] op_sel_hi:[1,0]
	v_pk_mul_f32 v[80:81], v[80:81], v[34:35] op_sel_hi:[1,0]
	v_pk_mul_f32 v[78:79], v[78:79], v[34:35] op_sel_hi:[1,0]
	v_pk_mul_f32 v[76:77], v[76:77], v[34:35] op_sel_hi:[1,0]
	v_pk_mul_f32 v[74:75], v[74:75], v[34:35] op_sel_hi:[1,0]
	v_pk_mul_f32 v[72:73], v[72:73], v[34:35] op_sel_hi:[1,0]
	v_pk_mul_f32 v[70:71], v[70:71], v[34:35] op_sel_hi:[1,0]
	v_pk_mul_f32 v[68:69], v[68:69], v[34:35] op_sel_hi:[1,0]
	v_pk_mul_f32 v[66:67], v[66:67], v[34:35] op_sel_hi:[1,0]
	v_sub_f32_e32 v2, v2, v248
	v_sub_f32_e32 v3, v3, v248
	v_sub_f32_e32 v4, v4, v248
	v_sub_f32_e32 v5, v5, v248
	v_sub_f32_e32 v6, v6, v248
	v_sub_f32_e32 v7, v7, v248
	v_sub_f32_e32 v8, v8, v248
	v_sub_f32_e32 v9, v9, v248
	v_sub_f32_e32 v10, v10, v248
	v_sub_f32_e32 v11, v11, v248
	v_sub_f32_e32 v12, v12, v248
	v_sub_f32_e32 v13, v13, v248
	v_sub_f32_e32 v14, v14, v248
	v_sub_f32_e32 v15, v15, v248
	v_sub_f32_e32 v16, v16, v248
	v_sub_f32_e32 v17, v17, v248
	v_sub_f32_e32 v18, v18, v248
	v_sub_f32_e32 v19, v19, v248
	v_sub_f32_e32 v20, v20, v248
	v_sub_f32_e32 v21, v21, v248
	v_sub_f32_e32 v22, v22, v248
	v_sub_f32_e32 v23, v23, v248
	v_sub_f32_e32 v24, v24, v248
	v_sub_f32_e32 v25, v25, v248
	v_sub_f32_e32 v26, v26, v248
	v_sub_f32_e32 v27, v27, v248
	v_sub_f32_e32 v28, v28, v248
	v_sub_f32_e32 v29, v29, v248
	v_sub_f32_e32 v30, v30, v248
	v_sub_f32_e32 v31, v31, v248
	v_sub_f32_e32 v32, v32, v248
	v_sub_f32_e32 v33, v33, v248
	v_sub_f32_e32 v232, v232, v248
	v_sub_f32_e32 v233, v233, v248
	v_sub_f32_e32 v234, v234, v248
	v_sub_f32_e32 v235, v235, v248
	v_sub_f32_e32 v236, v236, v248
	v_sub_f32_e32 v237, v237, v248
	v_sub_f32_e32 v238, v238, v248
	v_sub_f32_e32 v239, v239, v248
	v_sub_f32_e32 v240, v240, v248
	v_sub_f32_e32 v241, v241, v248
	v_sub_f32_e32 v242, v242, v248
	v_sub_f32_e32 v243, v243, v248
	v_sub_f32_e32 v244, v244, v248
	v_sub_f32_e32 v245, v245, v248
	v_sub_f32_e32 v246, v246, v248
	v_sub_f32_e32 v247, v247, v248
.LBB0_2991:
	s_add_i32 s8, s8, 0
	v_add3_u32 v99, s8, v217, v188
	ds_read_b128 v[34:37], v99 offset:21504
	ds_read_b128 v[50:53], v99 offset:28160
	ds_read_b128 v[100:103], v99 offset:21536
	s_waitcnt lgkmcnt(1)
	v_mfma_f32_32x32x16_bf16 v[50:65], v[50:53], v[134:137], v[232:247]
	ds_read_b128 v[104:107], v99 offset:28192
	v_exp_f32_e32 v2, v2
	v_exp_f32_e32 v18, v18
	v_exp_f32_e32 v3, v3
	v_mfma_f32_32x32x16_bf16 v[34:49], v[34:37], v[134:137], v[232:247]
	v_exp_f32_e32 v19, v19
	s_waitcnt lgkmcnt(1)
	v_mfma_f32_32x32x16_bf16 v[34:49], v[100:103], v[138:141], v[34:49]
	ds_read_b128 v[108:111], v99 offset:21568
	ds_read_b128 v[112:115], v99 offset:28224
	s_waitcnt lgkmcnt(2)
	v_mfma_f32_32x32x16_bf16 v[50:65], v[104:107], v[138:141], v[50:65]
	v_exp_f32_e32 v4, v4
	v_exp_f32_e32 v20, v20
	v_exp_f32_e32 v5, v5
	v_exp_f32_e32 v21, v21
	v_exp_f32_e32 v6, v6
	v_exp_f32_e32 v22, v22
	v_exp_f32_e32 v7, v7
	v_exp_f32_e32 v23, v23
	s_waitcnt lgkmcnt(1)
	v_mfma_f32_32x32x16_bf16 v[34:49], v[108:111], v[142:145], v[34:49]
	ds_read_b128 v[100:103], v99 offset:21600
	ds_read_b128 v[104:107], v99 offset:28256
	v_exp_f32_e32 v8, v8
	s_waitcnt lgkmcnt(2)
	v_mfma_f32_32x32x16_bf16 v[50:65], v[112:115], v[142:145], v[50:65]
	v_exp_f32_e32 v24, v24
	v_exp_f32_e32 v9, v9
	v_exp_f32_e32 v25, v25
	s_waitcnt lgkmcnt(1)
	v_mfma_f32_32x32x16_bf16 v[34:49], v[100:103], v[146:149], v[34:49]
	ds_read_b128 v[108:111], v99 offset:21632
	ds_read_b128 v[112:115], v99 offset:28288
	v_exp_f32_e32 v10, v10
	s_waitcnt lgkmcnt(2)
	v_mfma_f32_32x32x16_bf16 v[50:65], v[104:107], v[146:149], v[50:65]
	v_exp_f32_e32 v26, v26
	v_exp_f32_e32 v11, v11
	v_exp_f32_e32 v27, v27
	s_waitcnt lgkmcnt(1)
	v_mfma_f32_32x32x16_bf16 v[34:49], v[108:111], v[150:153], v[34:49]
	ds_read_b128 v[100:103], v99 offset:21664
	ds_read_b128 v[104:107], v99 offset:28320
	s_waitcnt lgkmcnt(2)
; #define LAS __attribute__((address_space(3)))
; __device__ __forceinline__ void att_qk_exp(const LAS char* kb, const bf16x8 (&qf)[6], float nm, fa::f32x16& n0, fa::f32x16& n1, fa::f32x16& p0, fa::f32x16& p1, float& lsum, bf16x8 (&pf)[4]) {
;     ...
; #pragma unroll
;         for (int r = lo[st]; r < lo[st + 1]; ++r) {
;             p0[r] = __builtin_amdgcn_exp2f(vadd1(p0[r], nm)); p1[r] = __builtin_amdgcn_exp2f(vadd1(p1[r], nm));
;             ps += p0[r]; ps += p1[r]; }
;         kc0 = kn0; kc1 = kn1;
;         __builtin_amdgcn_sched_barrier(0);
;     }
;     lsum += ps + ps2;
;     pf[0] = fa::pack_p(p0, 0); pf[1] = fa::pack_p(p0, 8); pf[2] = fa::pack_p(p1, 0); pf[3] = fa::pack_p(p1, 8);
; }
; __device__ __forceinline__ void att_exp_pack(fa::f32x16& p0, fa::f32x16& p1, float nm, float& lsum, bf16x8 (&pf)[4]) {
;     float ps = 0.f, ps2 = 0.f;
; #pragma unroll
;     for (int r = 0; r < 16; ++r) { p0[r] = __builtin_amdgcn_exp2f(vadd1(p0[r], nm)); p1[r] = __builtin_amdgcn_exp2f(vadd1(p1[r], nm)); ps += p0[r]; ps += p1[r]; }
;     lsum += ps + ps2;
;     pf[0] = fa::pack_p(p0, 0); pf[1] = fa::pack_p(p0, 8); pf[2] = fa::pack_p(p1, 0); pf[3] = fa::pack_p(p1, 8);
; }
; __device__ __forceinline__ float att_pv_max(fa::f32x16& o0, fa::f32x16& o1, const LAS char* vb, const bf16x8 (&pf)[4], const fa::f32x16& n0, const fa::f32x16& n1) {
;     using namespace fa;
;     float ta = n0[0], tb = n1[0];
;     s16x4 a0 = vtr(vb), a1 = vtr(vb + 512), b0 = vtr(vb + 4096), b1 = vtr(vb + 4096 + 512);
; #pragma unroll
;     for (int ks = 0; ks < 4; ++ks) {
;         s16x4 na0 = a0, na1 = a1, nb0 = b0, nb1 = b1;
;         if (ks < 3) { na0 = vtr(vb + (ks + 1) * 1024); na1 = vtr(vb + (ks + 1) * 1024 + 512); nb0 = vtr(vb + 4096 + (ks + 1) * 1024); nb1 = vtr(vb + 4096 + (ks + 1) * 1024 + 512); }
;         const bf16x8 v0 = (bf16x8){a0[0], a0[1], a0[2], a0[3], a1[0], a1[1], a1[2], a1[3]}, v1 = (bf16x8){b0[0], b0[1], b0[2], b0[3], b1[0], b1[1], b1[2], b1[3]};
;         o0 = __builtin_amdgcn_mfma_f32_32x32x16_bf16(v0, pf[ks], o0, 0, 0, 0);
;         o1 = __builtin_amdgcn_mfma_f32_32x32x16_bf16(v1, pf[ks], o1, 0, 0, 0);
; #pragma unroll
;         for (int r = 4 * ks; r < 4 * ks + 4; ++r) { ta = fmaxf(ta, n0[r]); tb = fmaxf(tb, n1[r]); }
;         a0 = na0; a1 = na1; b0 = nb0; b1 = nb1;
;         __builtin_amdgcn_sched_barrier(0);
;     }
;     return fmaxf(ta, tb);
; }
	v_mfma_f32_32x32x16_bf16 v[50:65], v[112:115], v[150:153], v[50:65]
	v_exp_f32_e32 v12, v12
	v_exp_f32_e32 v28, v28
	v_exp_f32_e32 v13, v13
	v_exp_f32_e32 v29, v29
	v_exp_f32_e32 v14, v14
	v_exp_f32_e32 v30, v30
	v_exp_f32_e32 v15, v15
	v_exp_f32_e32 v31, v31
	v_add_f32_e32 v99, v18, v2
	v_add_f32_e32 v99, v99, v3
	v_add_f32_e32 v99, v19, v99
	v_add_f32_e32 v99, v99, v4
	v_add_f32_e32 v99, v20, v99
	v_add_f32_e32 v99, v99, v5
	v_add_f32_e32 v99, v21, v99
	v_add_f32_e32 v99, v99, v6
	v_add_f32_e32 v99, v22, v99
	v_add_f32_e32 v99, v99, v7
	v_add_f32_e32 v99, v23, v99
	v_add_f32_e32 v99, v99, v8
	v_add_f32_e32 v99, v24, v99
	v_add_f32_e32 v99, v99, v9
	v_add_f32_e32 v99, v25, v99
	v_add_f32_e32 v99, v99, v10
	v_add_f32_e32 v99, v26, v99
	v_add_f32_e32 v99, v99, v11
	v_add_f32_e32 v99, v27, v99
	v_add_f32_e32 v99, v99, v12
	v_add_f32_e32 v99, v28, v99
	v_add_f32_e32 v99, v99, v13
	v_add_f32_e32 v99, v29, v99
	v_exp_f32_e32 v16, v16
	s_waitcnt lgkmcnt(1)
	v_mfma_f32_32x32x16_bf16 v[34:49], v[100:103], v[154:157], v[34:49]
	v_add_f32_e32 v99, v99, v14
	v_exp_f32_e32 v32, v32
	v_add_f32_e32 v99, v30, v99
	v_exp_f32_e32 v17, v17
	v_add_f32_e32 v99, v99, v15
	s_waitcnt lgkmcnt(0)
	v_mfma_f32_32x32x16_bf16 v[50:65], v[104:107], v[154:157], v[50:65]
	v_exp_f32_e32 v33, v33
	v_add_f32_e32 v99, v31, v99
	v_add_f32_e32 v99, v99, v16
	v_add_f32_e32 v99, v32, v99
	v_add_f32_e32 v99, v99, v17
	v_add_f32_e32 v99, v33, v99
	v_add_u32_e32 v221, s8, v216
	v_cvt_pk_bf16_f32 v100, v2, v3
	v_cvt_pk_bf16_f32 v101, v4, v5
	v_cvt_pk_bf16_f32 v102, v6, v7
	v_cvt_pk_bf16_f32 v103, v8, v9
	v_cvt_pk_bf16_f32 v104, v10, v11
	v_cvt_pk_bf16_f32 v105, v12, v13
	v_cvt_pk_bf16_f32 v106, v14, v15
	v_cvt_pk_bf16_f32 v107, v16, v17
	v_cvt_pk_bf16_f32 v108, v18, v19
	v_cvt_pk_bf16_f32 v109, v20, v21
	v_cvt_pk_bf16_f32 v110, v22, v23
	v_cvt_pk_bf16_f32 v111, v24, v25
	v_cvt_pk_bf16_f32 v224, v26, v27
	v_cvt_pk_bf16_f32 v225, v28, v29
	v_cvt_pk_bf16_f32 v226, v30, v31
	v_cvt_pk_bf16_f32 v227, v32, v33
	ds_read_b64_tr_b16 v[112:113], v221 offset:13312
	ds_read_b64_tr_b16 v[114:115], v221 offset:13824
	ds_read_b64_tr_b16 v[116:117], v221 offset:14336
	ds_read_b64_tr_b16 v[118:119], v221 offset:14848
	s_waitcnt lgkmcnt(2)
	v_mfma_f32_32x32x16_bf16 v[82:97], v[112:115], v[100:103], v[82:97]
	ds_read_b64_tr_b16 v[112:113], v221 offset:17408
	ds_read_b64_tr_b16 v[114:115], v221 offset:17920
	ds_read_b64_tr_b16 v[120:121], v221 offset:18432
	ds_read_b64_tr_b16 v[122:123], v221 offset:18944
	v_add_f32_e32 v220, v98, v99
	s_waitcnt lgkmcnt(2)
	v_mfma_f32_32x32x16_bf16 v[66:81], v[112:115], v[100:103], v[66:81]
	s_waitcnt lgkmcnt(0)
	v_mfma_f32_32x32x16_bf16 v[66:81], v[120:123], v[104:107], v[66:81]
	ds_read_b64_tr_b16 v[98:99], v221 offset:15360
	ds_read_b64_tr_b16 v[100:101], v221 offset:15872
	ds_read_b64_tr_b16 v[112:113], v221 offset:19456
	ds_read_b64_tr_b16 v[114:115], v221 offset:19968
	v_mfma_f32_32x32x16_bf16 v[82:97], v[116:119], v[104:107], v[82:97]
	s_waitcnt lgkmcnt(0)
	v_mfma_f32_32x32x16_bf16 v[66:81], v[112:115], v[108:111], v[66:81]
	ds_read_b64_tr_b16 v[116:117], v221 offset:16384
	ds_read_b64_tr_b16 v[118:119], v221 offset:16896
	ds_read_b64_tr_b16 v[228:229], v221 offset:20480
	ds_read_b64_tr_b16 v[230:231], v221 offset:20992
	v_mfma_f32_32x32x16_bf16 v[82:97], v[98:101], v[108:111], v[82:97]
	v_max_f32_e32 v98, v51, v51
	v_max_f32_e32 v99, v50, v50
	v_max_f32_e32 v98, v99, v98
	v_max3_f32 v98, v98, v52, v53
	v_max3_f32 v98, v98, v54, v55
	v_max3_f32 v98, v98, v56, v57
	v_max3_f32 v114, v98, v58, v59
	v_max3_f32 v98, v114, v60, v61
	v_max3_f32 v99, v34, v35, v36
	s_waitcnt lgkmcnt(2)
	v_mfma_f32_32x32x16_bf16 v[82:97], v[116:119], v[224:227], v[82:97]
	v_max3_f32 v99, v99, v37, v38
	v_max3_f32 v99, v99, v39, v40
	s_waitcnt lgkmcnt(0)
	v_mfma_f32_32x32x16_bf16 v[66:81], v[228:231], v[224:227], v[66:81]
	v_max3_f32 v99, v99, v41, v42
	v_max3_f32 v99, v99, v43, v44
	v_max3_f32 v114, v99, v45, v46
	v_max3_f32 v115, v98, v62, v63
	v_max3_f32 v114, v114, v47, v48
	v_max3_f32 v115, v115, v64, v65
	v_max3_f32 v114, v114, v49, v115
	v_cmp_lt_f32_e32 vcc, 0x41000000, v114
	s_cbranch_vccz .LBB0_2993
	v_and_b32_e32 v116, 64, v1
	v_xor_b32_e32 v115, 32, v1
	v_add_u32_e32 v116, 64, v116
	v_cmp_lt_i32_e32 vcc, v115, v116
	s_nop 1
	v_cndmask_b32_e32 v115, v1, v115, vcc
	v_lshlrev_b32_e32 v115, 2, v115
	ds_bpermute_b32 v115, v115, v114
	v_max_f32_e32 v114, v114, v114
	s_waitcnt lgkmcnt(0)
; #define LAS __attribute__((address_space(3)))
; __device__ __forceinline__ void att_shift(float tm, bool first, float& mrun, float& lsum, fa::f32x16& o0, fa::f32x16& o1) {
;     if (first || __any(tm > mrun + 8.f)) {
;         tm = fmaxf(tm, __shfl_xor(tm, 32));
;         const float dl = first ? 0.f : fmaxf(tm - mrun, 0.f), alpha = __builtin_amdgcn_exp2f(-dl);
;         mrun = first ? tm : mrun + dl; lsum *= alpha;
; #pragma unroll
;         for (int r = 0; r < 16; ++r) { o0[r] *= alpha; o1[r] *= alpha; }
;     }
; }
; __device__ __forceinline__ void att_qk_exp(const LAS char* kb, const bf16x8 (&qf)[6], float nm, fa::f32x16& n0, fa::f32x16& n1, fa::f32x16& p0, fa::f32x16& p1, float& lsum, bf16x8 (&pf)[4]) {
;     const fa::f32x16 zero = {0.f, 0.f, 0.f, 0.f, 0.f, 0.f, 0.f, 0.f, 0.f, 0.f, 0.f, 0.f, 0.f, 0.f, 0.f, 0.f};
;     bf16x8 kc0 = *(const LAS bf16x8*)kb, kc1 = *(const LAS bf16x8*)(kb + 32 * fa::KP_A);
;     float ps = 0.f, ps2 = 0.f;
; #pragma unroll
;     for (int st = 0; st < 6; ++st) {
;         bf16x8 kn0 = kc0, kn1 = kc1;
;         if (st < 5) { kn0 = *(const LAS bf16x8*)(kb + 32 * (st + 1)); kn1 = *(const LAS bf16x8*)(kb + 32 * fa::KP_A + 32 * (st + 1)); }
;         n0 = __builtin_amdgcn_mfma_f32_32x32x16_bf16(kc0, qf[st], st == 0 ? zero : n0, 0, 0, 0);
;         n1 = __builtin_amdgcn_mfma_f32_32x32x16_bf16(kc1, qf[st], st == 0 ? zero : n1, 0, 0, 0);
;         constexpr int lo[7] = {0, 2, 6, 8, 10, 14, 16};
; #pragma unroll
;         for (int r = lo[st]; r < lo[st + 1]; ++r) {
;             p0[r] = __builtin_amdgcn_exp2f(vadd1(p0[r], nm)); p1[r] = __builtin_amdgcn_exp2f(vadd1(p1[r], nm));
;             ps += p0[r]; ps += p1[r]; }
;         kc0 = kn0; kc1 = kn1;
;         __builtin_amdgcn_sched_barrier(0);
;     }
;     lsum += ps + ps2;
;     pf[0] = fa::pack_p(p0, 0); pf[1] = fa::pack_p(p0, 8); pf[2] = fa::pack_p(p1, 0); pf[3] = fa::pack_p(p1, 8);
; }
; __device__ __forceinline__ void att_exp_pack(fa::f32x16& p0, fa::f32x16& p1, float nm, float& lsum, bf16x8 (&pf)[4]) {
;     float ps = 0.f, ps2 = 0.f;
; #pragma unroll
;     for (int r = 0; r < 16; ++r) { p0[r] = __builtin_amdgcn_exp2f(vadd1(p0[r], nm)); p1[r] = __builtin_amdgcn_exp2f(vadd1(p1[r], nm)); ps += p0[r]; ps += p1[r]; }
;     lsum += ps + ps2;
;     pf[0] = fa::pack_p(p0, 0); pf[1] = fa::pack_p(p0, 8); pf[2] = fa::pack_p(p1, 0); pf[3] = fa::pack_p(p1, 8);
; }
	v_max_f32_e32 v115, v115, v115
	v_max_f32_e32 v114, v114, v115
	v_max_f32_e32 v115, 0, v114
	v_exp_f32_e64 v114, -v115
	v_add_f32_e32 v131, v131, v115
	v_mul_f32_e32 v220, v220, v114
	v_pk_mul_f32 v[96:97], v[96:97], v[114:115] op_sel_hi:[1,0]
	v_pk_mul_f32 v[94:95], v[94:95], v[114:115] op_sel_hi:[1,0]
	v_pk_mul_f32 v[92:93], v[92:93], v[114:115] op_sel_hi:[1,0]
	v_pk_mul_f32 v[90:91], v[90:91], v[114:115] op_sel_hi:[1,0]
	v_pk_mul_f32 v[88:89], v[88:89], v[114:115] op_sel_hi:[1,0]
	v_pk_mul_f32 v[86:87], v[86:87], v[114:115] op_sel_hi:[1,0]
	v_pk_mul_f32 v[84:85], v[84:85], v[114:115] op_sel_hi:[1,0]
	v_pk_mul_f32 v[82:83], v[82:83], v[114:115] op_sel_hi:[1,0]
	v_pk_mul_f32 v[80:81], v[80:81], v[114:115] op_sel_hi:[1,0]
	v_pk_mul_f32 v[78:79], v[78:79], v[114:115] op_sel_hi:[1,0]
	v_pk_mul_f32 v[76:77], v[76:77], v[114:115] op_sel_hi:[1,0]
	v_pk_mul_f32 v[74:75], v[74:75], v[114:115] op_sel_hi:[1,0]
	v_pk_mul_f32 v[72:73], v[72:73], v[114:115] op_sel_hi:[1,0]
	v_pk_mul_f32 v[70:71], v[70:71], v[114:115] op_sel_hi:[1,0]
	v_pk_mul_f32 v[68:69], v[68:69], v[114:115] op_sel_hi:[1,0]
	v_pk_mul_f32 v[66:67], v[66:67], v[114:115] op_sel_hi:[1,0]
	v_sub_f32_e32 v34, v34, v115
	v_sub_f32_e32 v35, v35, v115
	v_sub_f32_e32 v36, v36, v115
	v_sub_f32_e32 v37, v37, v115
	v_sub_f32_e32 v38, v38, v115
	v_sub_f32_e32 v39, v39, v115
	v_sub_f32_e32 v40, v40, v115
	v_sub_f32_e32 v41, v41, v115
	v_sub_f32_e32 v42, v42, v115
	v_sub_f32_e32 v43, v43, v115
	v_sub_f32_e32 v44, v44, v115
	v_sub_f32_e32 v45, v45, v115
	v_sub_f32_e32 v46, v46, v115
	v_sub_f32_e32 v47, v47, v115
	v_sub_f32_e32 v48, v48, v115
	v_sub_f32_e32 v49, v49, v115
	v_sub_f32_e32 v50, v50, v115
	v_sub_f32_e32 v51, v51, v115
	v_sub_f32_e32 v52, v52, v115
	v_sub_f32_e32 v53, v53, v115
	v_sub_f32_e32 v54, v54, v115
	v_sub_f32_e32 v55, v55, v115
	v_sub_f32_e32 v56, v56, v115
	v_sub_f32_e32 v57, v57, v115
	v_sub_f32_e32 v58, v58, v115
	v_sub_f32_e32 v59, v59, v115
	v_sub_f32_e32 v60, v60, v115
	v_sub_f32_e32 v61, v61, v115
	v_sub_f32_e32 v62, v62, v115
	v_sub_f32_e32 v63, v63, v115
	v_sub_f32_e32 v64, v64, v115
	v_sub_f32_e32 v65, v65, v115
	v_sub_f32_e32 v232, v232, v115
	v_sub_f32_e32 v233, v233, v115
	v_sub_f32_e32 v234, v234, v115
	v_sub_f32_e32 v235, v235, v115
	v_sub_f32_e32 v236, v236, v115
	v_sub_f32_e32 v237, v237, v115
	v_sub_f32_e32 v238, v238, v115
	v_sub_f32_e32 v239, v239, v115
	v_sub_f32_e32 v240, v240, v115
	v_sub_f32_e32 v241, v241, v115
	v_sub_f32_e32 v242, v242, v115
	v_sub_f32_e32 v243, v243, v115
	v_sub_f32_e32 v244, v244, v115
	v_sub_f32_e32 v245, v245, v115
	v_sub_f32_e32 v246, v246, v115
	v_sub_f32_e32 v247, v247, v115
.LBB0_2993:
	s_mov_b64 s[8:9], -1
	s_and_b64 vcc, exec, s[12:13]
	s_barrier
	s_cbranch_vccz .LBB0_2995
	v_exp_f32_e32 v114, v34
	v_exp_f32_e32 v115, v50
	v_exp_f32_e32 v117, v35
	v_exp_f32_e32 v118, v51
	v_add_f32_e32 v116, 0, v114
	v_exp_f32_e32 v119, v36
	v_add_f32_e32 v116, v115, v116
	v_exp_f32_e32 v120, v52
	v_add_f32_e32 v116, v116, v117
	v_exp_f32_e32 v121, v37
	v_add_f32_e32 v116, v118, v116
	v_exp_f32_e32 v122, v53
	v_add_f32_e32 v116, v116, v119
	v_exp_f32_e32 v123, v38
	v_add_f32_e32 v116, v120, v116
	v_exp_f32_e32 v124, v54
	v_add_f32_e32 v116, v116, v121
	v_exp_f32_e32 v125, v39
	v_add_f32_e32 v116, v122, v116
	v_exp_f32_e32 v126, v55
	v_add_f32_e32 v116, v116, v123
	v_exp_f32_e32 v127, v40
	v_add_f32_e32 v116, v124, v116
	v_exp_f32_e32 v128, v56
	v_add_f32_e32 v116, v116, v125
	v_exp_f32_e32 v129, v41
	v_add_f32_e32 v116, v126, v116
	v_exp_f32_e32 v98, v57
	v_add_f32_e32 v116, v116, v127
	v_exp_f32_e32 v99, v42
	v_add_f32_e32 v116, v128, v116
	v_exp_f32_e32 v100, v58
	v_add_f32_e32 v116, v116, v129
	v_exp_f32_e32 v101, v43
	v_add_f32_e32 v116, v98, v116
	v_exp_f32_e32 v102, v59
	v_add_f32_e32 v116, v116, v99
	v_exp_f32_e32 v103, v44
	v_add_f32_e32 v116, v100, v116
	v_exp_f32_e32 v104, v60
	v_add_f32_e32 v116, v116, v101
	v_exp_f32_e32 v105, v45
	v_add_f32_e32 v116, v102, v116
	v_exp_f32_e32 v106, v61
	v_add_f32_e32 v116, v116, v103
	v_exp_f32_e32 v107, v46
	v_add_f32_e32 v116, v104, v116
	v_exp_f32_e32 v108, v62
	v_add_f32_e32 v116, v116, v105
	v_exp_f32_e32 v109, v47
	v_add_f32_e32 v116, v106, v116
	v_exp_f32_e32 v110, v63
	v_add_f32_e32 v116, v116, v107
	v_exp_f32_e32 v111, v48
	v_add_f32_e32 v116, v108, v116
	v_exp_f32_e32 v112, v64
	v_add_f32_e32 v116, v116, v109
	v_exp_f32_e32 v113, v49
	v_add_f32_e32 v116, v110, v116
	v_add_f32_e32 v116, v116, v111
	v_exp_f32_e32 v173, v65
	v_add_f32_e32 v116, v112, v116
	v_add_f32_e32 v116, v116, v113
	v_cvt_pk_bf16_f32 v224, v114, v117
	v_add_f32_e32 v223, v173, v116
	v_cvt_pk_bf16_f32 v225, v119, v121
	v_cvt_pk_bf16_f32 v226, v123, v125
	v_cvt_pk_bf16_f32 v227, v127, v129
	v_cvt_pk_bf16_f32 v228, v99, v101
	v_cvt_pk_bf16_f32 v229, v103, v105
	v_cvt_pk_bf16_f32 v230, v107, v109
	v_cvt_pk_bf16_f32 v231, v111, v113
	v_cvt_pk_bf16_f32 v166, v115, v118
	v_cvt_pk_bf16_f32 v167, v120, v122
	v_cvt_pk_bf16_f32 v168, v124, v126
	v_cvt_pk_bf16_f32 v169, v128, v98
	v_cvt_pk_bf16_f32 v170, v100, v102
	v_cvt_pk_bf16_f32 v171, v104, v106
	v_cvt_pk_bf16_f32 v172, v108, v110
	v_cvt_pk_bf16_f32 v173, v112, v173
	ds_read_b64_tr_b16 v[114:115], v221 offset:34816
	ds_read_b64_tr_b16 v[116:117], v221 offset:35328
	ds_read_b64_tr_b16 v[174:175], v221 offset:38912
	ds_read_b64_tr_b16 v[176:177], v221 offset:39424
	s_waitcnt lgkmcnt(2)
	v_mfma_f32_32x32x16_bf16 v[82:97], v[114:117], v[224:227], v[82:97]
	s_mov_b64 s[8:9], 0
	s_waitcnt lgkmcnt(0)
	v_mfma_f32_32x32x16_bf16 v[66:81], v[174:177], v[224:227], v[66:81]
	ds_read_b64_tr_b16 v[224:225], v221 offset:35840
	ds_read_b64_tr_b16 v[226:227], v221 offset:36352
	ds_read_b64_tr_b16 v[174:175], v221 offset:39936
	ds_read_b64_tr_b16 v[176:177], v221 offset:40448
	s_waitcnt lgkmcnt(2)
	v_mfma_f32_32x32x16_bf16 v[82:97], v[224:227], v[228:231], v[82:97]
	s_waitcnt lgkmcnt(0)
	v_mfma_f32_32x32x16_bf16 v[66:81], v[174:177], v[228:231], v[66:81]
	ds_read_b64_tr_b16 v[224:225], v221 offset:36864
	ds_read_b64_tr_b16 v[226:227], v221 offset:37376
	ds_read_b64_tr_b16 v[228:229], v221 offset:40960
	ds_read_b64_tr_b16 v[230:231], v221 offset:41472
	s_waitcnt lgkmcnt(2)
	v_mfma_f32_32x32x16_bf16 v[82:97], v[224:227], v[166:169], v[82:97]
	s_waitcnt lgkmcnt(0)
	v_mfma_f32_32x32x16_bf16 v[66:81], v[228:231], v[166:169], v[66:81]
	ds_read_b64_tr_b16 v[224:225], v221 offset:37888
	ds_read_b64_tr_b16 v[226:227], v221 offset:38400
	ds_read_b64_tr_b16 v[228:229], v221 offset:41984
	ds_read_b64_tr_b16 v[230:231], v221 offset:42496
	s_waitcnt lgkmcnt(2)
	v_mfma_f32_32x32x16_bf16 v[82:97], v[224:227], v[170:173], v[82:97]
	s_waitcnt lgkmcnt(0)
	v_mfma_f32_32x32x16_bf16 v[66:81], v[228:231], v[170:173], v[66:81]
; #define LAS __attribute__((address_space(3)))
; __device__ __forceinline__ void att_qk_exp(const LAS char* kb, const bf16x8 (&qf)[6], float nm, fa::f32x16& n0, fa::f32x16& n1, fa::f32x16& p0, fa::f32x16& p1, float& lsum, bf16x8 (&pf)[4]) {
;     const fa::f32x16 zero = {0.f, 0.f, 0.f, 0.f, 0.f, 0.f, 0.f, 0.f, 0.f, 0.f, 0.f, 0.f, 0.f, 0.f, 0.f, 0.f};
;     bf16x8 kc0 = *(const LAS bf16x8*)kb, kc1 = *(const LAS bf16x8*)(kb + 32 * fa::KP_A);
;     float ps = 0.f, ps2 = 0.f;
; #pragma unroll
;     for (int st = 0; st < 6; ++st) {
;         bf16x8 kn0 = kc0, kn1 = kc1;
;         if (st < 5) { kn0 = *(const LAS bf16x8*)(kb + 32 * (st + 1)); kn1 = *(const LAS bf16x8*)(kb + 32 * fa::KP_A + 32 * (st + 1)); }
;         n0 = __builtin_amdgcn_mfma_f32_32x32x16_bf16(kc0, qf[st], st == 0 ? zero : n0, 0, 0, 0);
;         n1 = __builtin_amdgcn_mfma_f32_32x32x16_bf16(kc1, qf[st], st == 0 ? zero : n1, 0, 0, 0);
;         constexpr int lo[7] = {0, 2, 6, 8, 10, 14, 16};
; #pragma unroll
;         for (int r = lo[st]; r < lo[st + 1]; ++r) {
;             p0[r] = __builtin_amdgcn_exp2f(vadd1(p0[r], nm)); p1[r] = __builtin_amdgcn_exp2f(vadd1(p1[r], nm));
;             ps += p0[r]; ps += p1[r]; }
;         kc0 = kn0; kc1 = kn1;
;         __builtin_amdgcn_sched_barrier(0);
;     }
;     lsum += ps + ps2;
;     pf[0] = fa::pack_p(p0, 0); pf[1] = fa::pack_p(p0, 8); pf[2] = fa::pack_p(p1, 0); pf[3] = fa::pack_p(p1, 8);
; }
; __device__ __forceinline__ void att_exp_pack(fa::f32x16& p0, fa::f32x16& p1, float nm, float& lsum, bf16x8 (&pf)[4]) {
;     float ps = 0.f, ps2 = 0.f;
; #pragma unroll
;     for (int r = 0; r < 16; ++r) { p0[r] = __builtin_amdgcn_exp2f(vadd1(p0[r], nm)); p1[r] = __builtin_amdgcn_exp2f(vadd1(p1[r], nm)); ps += p0[r]; ps += p1[r]; }
;     lsum += ps + ps2;
;     pf[0] = fa::pack_p(p0, 0); pf[1] = fa::pack_p(p0, 8); pf[2] = fa::pack_p(p1, 0); pf[3] = fa::pack_p(p1, 8);
; }
; __device__ __forceinline__ float att_pv_max(fa::f32x16& o0, fa::f32x16& o1, const LAS char* vb, const bf16x8 (&pf)[4], const fa::f32x16& n0, const fa::f32x16& n1) {
;     using namespace fa;
;     float ta = n0[0], tb = n1[0];
;     s16x4 a0 = vtr(vb), a1 = vtr(vb + 512), b0 = vtr(vb + 4096), b1 = vtr(vb + 4096 + 512);
; #pragma unroll
;     for (int ks = 0; ks < 4; ++ks) {
;         s16x4 na0 = a0, na1 = a1, nb0 = b0, nb1 = b1;
.LBB0_2995:
	s_andn2_b64 vcc, exec, s[8:9]
	s_cbranch_vccnz .LBB0_2997
	v_add_u32_e32 v98, s19, v218
	ds_read_b128 v[2:5], v98
	ds_read_b128 v[18:21], v98 offset:6656
	ds_read_b128 v[114:117], v98 offset:32
	ds_read_b128 v[118:121], v98 offset:6688
	v_exp_f32_e32 v99, v34
	v_exp_f32_e32 v100, v50
	s_waitcnt lgkmcnt(3)
	v_mfma_f32_32x32x16_bf16 v[2:17], v[2:5], v[134:137], v[232:247]
	v_exp_f32_e32 v101, v35
	v_exp_f32_e32 v102, v51
	s_waitcnt lgkmcnt(2)
	v_mfma_f32_32x32x16_bf16 v[18:33], v[18:21], v[134:137], v[232:247]
	s_waitcnt lgkmcnt(1)
	v_mfma_f32_32x32x16_bf16 v[2:17], v[114:117], v[138:141], v[2:17]
	v_exp_f32_e32 v103, v36
	ds_read_b128 v[122:125], v98 offset:64
	ds_read_b128 v[126:129], v98 offset:6720
	v_exp_f32_e32 v104, v52
	v_exp_f32_e32 v114, v37
	s_waitcnt lgkmcnt(2)
	v_mfma_f32_32x32x16_bf16 v[18:33], v[118:121], v[138:141], v[18:33]
	v_exp_f32_e32 v115, v53
	v_exp_f32_e32 v116, v38
	v_exp_f32_e32 v117, v54
	v_exp_f32_e32 v105, v39
	v_exp_f32_e32 v106, v55
	s_waitcnt lgkmcnt(1)
	v_mfma_f32_32x32x16_bf16 v[2:17], v[122:125], v[142:145], v[2:17]
	ds_read_b128 v[34:37], v98 offset:96
	ds_read_b128 v[50:53], v98 offset:6752
	v_exp_f32_e32 v118, v40
	v_exp_f32_e32 v119, v56
	s_waitcnt lgkmcnt(2)
	v_mfma_f32_32x32x16_bf16 v[18:33], v[126:129], v[142:145], v[18:33]
	v_exp_f32_e32 v120, v41
	v_exp_f32_e32 v121, v57
	s_waitcnt lgkmcnt(1)
	v_mfma_f32_32x32x16_bf16 v[2:17], v[34:37], v[146:149], v[2:17]
	ds_read_b128 v[38:41], v98 offset:128
	ds_read_b128 v[54:57], v98 offset:6784
	v_exp_f32_e32 v42, v42
	v_exp_f32_e32 v58, v58
	s_waitcnt lgkmcnt(2)
	v_mfma_f32_32x32x16_bf16 v[18:33], v[50:53], v[146:149], v[18:33]
	v_exp_f32_e32 v43, v43
	v_exp_f32_e32 v59, v59
	s_waitcnt lgkmcnt(1)
	v_mfma_f32_32x32x16_bf16 v[2:17], v[38:41], v[150:153], v[2:17]
	ds_read_b128 v[34:37], v98 offset:160
	ds_read_b128 v[50:53], v98 offset:6816
	v_exp_f32_e32 v39, v45
	s_waitcnt lgkmcnt(2)
	v_mfma_f32_32x32x16_bf16 v[18:33], v[54:57], v[150:153], v[18:33]
	v_exp_f32_e32 v61, v61
	v_exp_f32_e32 v44, v44
	v_exp_f32_e32 v40, v46
	v_exp_f32_e32 v60, v60
	v_exp_f32_e32 v62, v62
	v_exp_f32_e32 v41, v47
	v_exp_f32_e32 v63, v63
	s_waitcnt lgkmcnt(1)
	v_mfma_f32_32x32x16_bf16 v[2:17], v[34:37], v[154:157], v[2:17]
	v_exp_f32_e32 v45, v48
	v_exp_f32_e32 v54, v64
	v_mov_b32_e32 v38, v49
	v_exp_f32_e32 v49, v65
	v_add_f32_e32 v34, v100, v99
	v_add_f32_e32 v34, v34, v101
	v_add_f32_e32 v34, v102, v34
	v_add_f32_e32 v34, v34, v103
	v_add_f32_e32 v34, v104, v34
	v_add_f32_e32 v34, v34, v114
	v_add_f32_e32 v34, v115, v34
	v_add_f32_e32 v34, v34, v116
	v_add_f32_e32 v34, v117, v34
	v_add_f32_e32 v34, v34, v105
	v_add_f32_e32 v34, v106, v34
	v_add_f32_e32 v34, v34, v118
	v_add_f32_e32 v34, v119, v34
	v_add_f32_e32 v34, v34, v120
	v_add_f32_e32 v34, v121, v34
	v_add_f32_e32 v34, v34, v42
	v_add_f32_e32 v34, v58, v34
	v_add_f32_e32 v34, v34, v43
	v_add_f32_e32 v34, v59, v34
	v_add_f32_e32 v34, v34, v44
	v_add_f32_e32 v34, v60, v34
	v_add_f32_e32 v34, v34, v39
	v_add_f32_e32 v34, v61, v34
	s_waitcnt lgkmcnt(0)
	v_mfma_f32_32x32x16_bf16 v[18:33], v[50:53], v[154:157], v[18:33]
	v_add_f32_e32 v34, v34, v40
	v_add_f32_e32 v34, v62, v34
	v_exp_f32_e32 v46, v38
	v_add_f32_e32 v34, v34, v41
	v_add_f32_e32 v34, v63, v34
	v_add_f32_e32 v34, v34, v45
	v_add_f32_e32 v34, v54, v34
	v_add_f32_e32 v34, v34, v46
	v_add_f32_e32 v223, v49, v34
	v_cvt_pk_bf16_f32 v34, v99, v101
	v_cvt_pk_bf16_f32 v35, v103, v114
	v_cvt_pk_bf16_f32 v36, v116, v105
	v_cvt_pk_bf16_f32 v37, v118, v120
	v_cvt_pk_bf16_f32 v38, v42, v43
	v_cvt_pk_bf16_f32 v39, v44, v39
	v_cvt_pk_bf16_f32 v40, v40, v41
	v_cvt_pk_bf16_f32 v41, v45, v46
	v_cvt_pk_bf16_f32 v42, v100, v102
	v_cvt_pk_bf16_f32 v43, v104, v115
	v_cvt_pk_bf16_f32 v44, v117, v106
	v_cvt_pk_bf16_f32 v45, v119, v121
	v_cvt_pk_bf16_f32 v46, v58, v59
	v_cvt_pk_bf16_f32 v47, v60, v61
	v_cvt_pk_bf16_f32 v48, v62, v63
	v_cvt_pk_bf16_f32 v49, v54, v49
	ds_read_b64_tr_b16 v[50:51], v221 offset:34816
	ds_read_b64_tr_b16 v[52:53], v221 offset:35328
	ds_read_b64_tr_b16 v[54:55], v221 offset:35840
	ds_read_b64_tr_b16 v[56:57], v221 offset:36352
	s_waitcnt lgkmcnt(2)
	v_mfma_f32_32x32x16_bf16 v[82:97], v[50:53], v[34:37], v[82:97]
	ds_read_b64_tr_b16 v[50:51], v221 offset:38912
	ds_read_b64_tr_b16 v[52:53], v221 offset:39424
	ds_read_b64_tr_b16 v[58:59], v221 offset:39936
	ds_read_b64_tr_b16 v[60:61], v221 offset:40448
	s_waitcnt lgkmcnt(2)
	v_mfma_f32_32x32x16_bf16 v[66:81], v[50:53], v[34:37], v[66:81]
	ds_read_b64_tr_b16 v[34:35], v221 offset:36864
	ds_read_b64_tr_b16 v[36:37], v221 offset:37376
	ds_read_b64_tr_b16 v[50:51], v221 offset:40960
	ds_read_b64_tr_b16 v[52:53], v221 offset:41472
	v_mfma_f32_32x32x16_bf16 v[82:97], v[54:57], v[38:41], v[82:97]
	s_waitcnt lgkmcnt(4)
	v_mfma_f32_32x32x16_bf16 v[66:81], v[58:61], v[38:41], v[66:81]
	s_waitcnt lgkmcnt(2)
	v_mfma_f32_32x32x16_bf16 v[82:97], v[34:37], v[42:45], v[82:97]
	ds_read_b64_tr_b16 v[34:35], v221 offset:37888
	ds_read_b64_tr_b16 v[36:37], v221 offset:38400
	ds_read_b64_tr_b16 v[38:39], v221 offset:41984
	ds_read_b64_tr_b16 v[40:41], v221 offset:42496
	s_waitcnt lgkmcnt(4)
	v_mfma_f32_32x32x16_bf16 v[66:81], v[50:53], v[42:45], v[66:81]
	v_max_f32_e32 v42, v19, v19
	v_max_f32_e32 v43, v18, v18
	v_max_f32_e32 v42, v43, v42
	v_max3_f32 v42, v42, v20, v21
	s_waitcnt lgkmcnt(2)
	v_mfma_f32_32x32x16_bf16 v[82:97], v[34:37], v[46:49], v[82:97]
	v_max3_f32 v35, v2, v3, v4
	v_max3_f32 v42, v42, v22, v23
	v_max3_f32 v35, v35, v5, v6
	v_max3_f32 v42, v42, v24, v25
	v_max3_f32 v35, v35, v7, v8
	v_max3_f32 v34, v42, v26, v27
	v_max3_f32 v35, v35, v9, v10
	v_max3_f32 v34, v34, v28, v29
	v_max3_f32 v35, v35, v11, v12
	v_max3_f32 v35, v35, v13, v14
	v_max3_f32 v34, v34, v30, v31
	s_waitcnt lgkmcnt(0)
	v_mfma_f32_32x32x16_bf16 v[66:81], v[38:41], v[46:49], v[66:81]
	v_max3_f32 v35, v35, v15, v16
	v_max3_f32 v34, v34, v32, v33
	v_max3_f32 v201, v35, v17, v34
